# added: final LayerNorm loads gamma/beta once and prefetches the next row (no per-chunk full waits on store acks); second-unit row-stat loads issued together
# speedup vs baseline: 1.0136x; 1.0013x over previous
.LBB0_849:
	s_or_b64 exec, exec, s[46:47]
	s_and_b64 vcc, exec, s[8:9]
	s_mov_b64 s[8:9], -1
	s_cbranch_vccnz .LBB0_818
	v_mov_b32_e32 v0, v153
	v_mov_b32_e32 v1, v151
	s_lshl_b32 s8, s78, 8
	s_add_i32 s8, s8, s13
	v_add_u32_e32 v0, s8, v0
	s_waitcnt lgkmcnt(0)
	v_lshlrev_b32_e32 v2, 3, v1
	v_ashrrev_i32_e32 v3, 31, v2
	v_ashrrev_i32_e32 v1, 31, v0
	v_lshl_add_u64 v[6:7], v[2:3], 2, s[62:63]
	v_lshlrev_b64 v[4:5], 7, v[0:1]
	v_lshl_add_u64 v[4:5], v[6:7], 0, v[4:5]
	v_mov_b32_e32 v100, v0
	v_ashrrev_i32_e32 v101, 31, v100
	v_lshlrev_b64 v[100:101], 7, v[100:101]
	v_lshl_add_u64 v[100:101], v[6:7], 0, v[100:101]
	global_load_dwordx4 v[104:107], v[100:101], off offset:16
	global_load_dwordx4 v[108:111], v[100:101], off
	v_add_u32_e32 v100, 0x10, v0
	v_ashrrev_i32_e32 v101, 31, v100
	v_lshlrev_b64 v[100:101], 7, v[100:101]
	v_lshl_add_u64 v[100:101], v[6:7], 0, v[100:101]
	global_load_dwordx4 v[124:127], v[100:101], off offset:16
	global_load_dwordx4 v[180:183], v[100:101], off
	v_add_u32_e32 v100, 0x20, v0
	v_ashrrev_i32_e32 v101, 31, v100
	v_lshlrev_b64 v[100:101], 7, v[100:101]
	v_lshl_add_u64 v[100:101], v[6:7], 0, v[100:101]
	global_load_dwordx4 v[184:187], v[100:101], off offset:16
	global_load_dwordx4 v[188:191], v[100:101], off
	v_add_u32_e32 v100, 0x30, v0
	v_ashrrev_i32_e32 v101, 31, v100
	v_lshlrev_b64 v[100:101], 7, v[100:101]
	v_lshl_add_u64 v[100:101], v[6:7], 0, v[100:101]
	global_load_dwordx4 v[192:195], v[100:101], off offset:16
	global_load_dwordx4 v[196:199], v[100:101], off
	v_add_u32_e32 v100, 0x80, v0
	v_ashrrev_i32_e32 v101, 31, v100
	v_lshlrev_b64 v[100:101], 7, v[100:101]
	v_lshl_add_u64 v[100:101], v[6:7], 0, v[100:101]
	global_load_dwordx4 v[200:203], v[100:101], off offset:16
	global_load_dwordx4 v[204:207], v[100:101], off
	v_add_u32_e32 v100, 0x90, v0
	v_ashrrev_i32_e32 v101, 31, v100
	v_lshlrev_b64 v[100:101], 7, v[100:101]
	v_lshl_add_u64 v[100:101], v[6:7], 0, v[100:101]
	global_load_dwordx4 v[208:211], v[100:101], off offset:16
	global_load_dwordx4 v[212:215], v[100:101], off
	v_add_u32_e32 v100, 0xa0, v0
	v_ashrrev_i32_e32 v101, 31, v100
	v_lshlrev_b64 v[100:101], 7, v[100:101]
	v_lshl_add_u64 v[100:101], v[6:7], 0, v[100:101]
	global_load_dwordx4 v[216:219], v[100:101], off offset:16
	global_load_dwordx4 v[220:223], v[100:101], off
	v_add_u32_e32 v100, 0xb0, v0
	v_ashrrev_i32_e32 v101, 31, v100
	v_lshlrev_b64 v[100:101], 7, v[100:101]
	v_lshl_add_u64 v[100:101], v[6:7], 0, v[100:101]
	global_load_dwordx4 v[224:227], v[100:101], off offset:16
	global_load_dwordx4 v[228:231], v[100:101], off
	s_waitcnt vmcnt(0)
	v_mov_b32_e32 v8, v104
	v_mov_b32_e32 v9, v105
	v_mov_b32_e32 v10, v106
	v_mov_b32_e32 v11, v107
	v_mov_b32_e32 v12, v108
	v_mov_b32_e32 v13, v109
	v_mov_b32_e32 v14, v110
	v_mov_b32_e32 v15, v111
	v_add_u32_e32 v56, 0x90, v0
	v_ashrrev_i32_e32 v57, 31, v56
	v_add_u32_e32 v58, 0xa0, v0
	v_ashrrev_i32_e32 v59, 31, v58
	v_add_u32_e32 v60, 0xb0, v0
	v_ashrrev_i32_e32 v61, 31, v60
	s_lshl_b32 s8, s73, 8
	s_or_b32 s8, s8, s66
	v_add_u32_e32 v2, s8, v2
	v_ashrrev_i32_e32 v3, 31, v2
	s_andn2_b64 vcc, exec, s[4:5]
	v_mov_b32_e32 v5, v8
	v_mov_b32_e32 v4, v12
	v_mov_b32_e32 v16, v14
	v_mov_b32_e32 v17, v10
	v_pk_add_f32 v[4:5], v[4:5], v[16:17]
	v_add_f32_e32 v8, v13, v15
	v_add_f32_e32 v10, v9, v11
	v_mov_b32_e32 v9, v4
	v_mov_b32_e32 v11, v5
	v_pk_add_f32 v[4:5], v[8:9], v[10:11]
	ds_bpermute_b32 v9, v155, v5
	ds_bpermute_b32 v8, v155, v4
	s_waitcnt lgkmcnt(0)
	v_pk_add_f32 v[48:49], v[4:5], v[8:9]
	v_add_u32_e32 v4, 16, v0
	v_ashrrev_i32_e32 v5, 31, v4
	v_lshlrev_b64 v[8:9], 7, v[4:5]
	v_lshl_add_u64 v[12:13], v[6:7], 0, v[8:9]
	v_mov_b32_e32 v8, v124
	v_mov_b32_e32 v9, v125
	v_mov_b32_e32 v10, v126
	v_mov_b32_e32 v11, v127
	s_nop 0
	v_mov_b32_e32 v12, v180
	v_mov_b32_e32 v13, v181
	v_mov_b32_e32 v14, v182
	v_mov_b32_e32 v15, v183
	ds_bpermute_b32 v51, v157, v49
	ds_bpermute_b32 v50, v157, v48
	v_mov_b32_e32 v17, v8
	v_mov_b32_e32 v16, v12
	v_mov_b32_e32 v18, v14
	v_mov_b32_e32 v19, v10
	v_pk_add_f32 v[16:17], v[16:17], v[18:19]
	v_add_f32_e32 v8, v13, v15
	v_add_f32_e32 v10, v9, v11
	v_mov_b32_e32 v9, v16
	v_mov_b32_e32 v11, v17
	v_pk_add_f32 v[8:9], v[8:9], v[10:11]
	ds_bpermute_b32 v11, v155, v9
	ds_bpermute_b32 v10, v155, v8
	s_waitcnt lgkmcnt(0)
	v_pk_add_f32 v[52:53], v[8:9], v[10:11]
	v_add_u32_e32 v8, 32, v0
	v_ashrrev_i32_e32 v9, 31, v8
	v_lshlrev_b64 v[10:11], 7, v[8:9]
	v_lshl_add_u64 v[14:15], v[6:7], 0, v[10:11]
	v_mov_b32_e32 v10, v184
	v_mov_b32_e32 v11, v185
	v_mov_b32_e32 v12, v186
	v_mov_b32_e32 v13, v187
	s_nop 0
	v_mov_b32_e32 v14, v188
	v_mov_b32_e32 v15, v189
	v_mov_b32_e32 v16, v190
	v_mov_b32_e32 v17, v191
	ds_bpermute_b32 v55, v157, v53
	ds_bpermute_b32 v54, v157, v52
	v_mov_b32_e32 v19, v10
	v_mov_b32_e32 v18, v14
	v_mov_b32_e32 v20, v16
	v_mov_b32_e32 v21, v12
	v_pk_add_f32 v[18:19], v[18:19], v[20:21]
	v_add_f32_e32 v10, v15, v17
	v_add_f32_e32 v12, v11, v13
	v_mov_b32_e32 v11, v18
	v_mov_b32_e32 v13, v19
	v_pk_add_f32 v[10:11], v[10:11], v[12:13]
	ds_bpermute_b32 v13, v155, v11
	ds_bpermute_b32 v12, v155, v10
	s_waitcnt lgkmcnt(0)
	v_pk_add_f32 v[64:65], v[10:11], v[12:13]
	v_add_u32_e32 v10, 48, v0
	v_ashrrev_i32_e32 v11, 31, v10
	v_lshlrev_b64 v[12:13], 7, v[10:11]
	v_lshl_add_u64 v[16:17], v[6:7], 0, v[12:13]
	v_mov_b32_e32 v12, v192
	v_mov_b32_e32 v13, v193
	v_mov_b32_e32 v14, v194
	v_mov_b32_e32 v15, v195
	s_nop 0
	v_mov_b32_e32 v16, v196
	v_mov_b32_e32 v17, v197
	v_mov_b32_e32 v18, v198
	v_mov_b32_e32 v19, v199
	ds_bpermute_b32 v67, v157, v65
	ds_bpermute_b32 v66, v157, v64
	v_mov_b32_e32 v21, v12
	v_mov_b32_e32 v20, v16
	v_mov_b32_e32 v22, v18
	v_mov_b32_e32 v23, v14
	v_pk_add_f32 v[20:21], v[20:21], v[22:23]
	v_add_f32_e32 v12, v17, v19
	v_add_f32_e32 v14, v13, v15
	v_mov_b32_e32 v13, v20
	v_mov_b32_e32 v15, v21
	v_pk_add_f32 v[12:13], v[12:13], v[14:15]
	ds_bpermute_b32 v15, v155, v13
	ds_bpermute_b32 v14, v155, v12
	s_waitcnt lgkmcnt(0)
	v_pk_add_f32 v[68:69], v[12:13], v[14:15]
	v_add_u32_e32 v12, 0x80, v0
	v_ashrrev_i32_e32 v13, 31, v12
	v_lshlrev_b64 v[14:15], 7, v[12:13]
	v_lshl_add_u64 v[18:19], v[6:7], 0, v[14:15]
	v_mov_b32_e32 v14, v200
	v_mov_b32_e32 v15, v201
	v_mov_b32_e32 v16, v202
	v_mov_b32_e32 v17, v203
	s_nop 0
	v_mov_b32_e32 v18, v204
	v_mov_b32_e32 v19, v205
	v_mov_b32_e32 v20, v206
	v_mov_b32_e32 v21, v207
	v_lshlrev_b64 v[0:1], 11, v[0:1]
	v_lshl_add_u64 v[0:1], s[44:45], 0, v[0:1]
	ds_bpermute_b32 v71, v157, v69
	ds_bpermute_b32 v70, v157, v68
	v_mov_b32_e32 v23, v14
	v_mov_b32_e32 v22, v18
	v_mov_b32_e32 v24, v20
	v_mov_b32_e32 v25, v16
	v_pk_add_f32 v[22:23], v[22:23], v[24:25]
	v_add_f32_e32 v14, v19, v21
	v_add_f32_e32 v16, v15, v17
	v_mov_b32_e32 v15, v22
	v_mov_b32_e32 v17, v23
	v_pk_add_f32 v[14:15], v[14:15], v[16:17]
	ds_bpermute_b32 v17, v155, v15
	ds_bpermute_b32 v16, v155, v14
	s_waitcnt lgkmcnt(0)
	v_pk_add_f32 v[112:113], v[14:15], v[16:17]
	v_lshlrev_b64 v[14:15], 7, v[56:57]
	v_lshl_add_u64 v[18:19], v[6:7], 0, v[14:15]
	v_mov_b32_e32 v14, v208
	v_mov_b32_e32 v15, v209
	v_mov_b32_e32 v16, v210
	v_mov_b32_e32 v17, v211
	s_nop 0
	v_mov_b32_e32 v18, v212
	v_mov_b32_e32 v19, v213
	v_mov_b32_e32 v20, v214
	v_mov_b32_e32 v21, v215
	ds_bpermute_b32 v115, v157, v113
	ds_bpermute_b32 v114, v157, v112
	v_mov_b32_e32 v23, v14
	v_mov_b32_e32 v22, v18
	v_mov_b32_e32 v24, v20
	v_mov_b32_e32 v25, v16
	v_pk_add_f32 v[22:23], v[22:23], v[24:25]
	v_add_f32_e32 v14, v19, v21
	v_add_f32_e32 v16, v15, v17
	v_mov_b32_e32 v15, v22
	v_mov_b32_e32 v17, v23
	v_pk_add_f32 v[14:15], v[14:15], v[16:17]
	ds_bpermute_b32 v17, v155, v15
	ds_bpermute_b32 v16, v155, v14
	s_waitcnt lgkmcnt(0)
	v_pk_add_f32 v[116:117], v[14:15], v[16:17]
	v_lshlrev_b64 v[14:15], 7, v[58:59]
	v_lshl_add_u64 v[18:19], v[6:7], 0, v[14:15]
	v_mov_b32_e32 v14, v216
	v_mov_b32_e32 v15, v217
	v_mov_b32_e32 v16, v218
	v_mov_b32_e32 v17, v219
	s_nop 0
	v_mov_b32_e32 v18, v220
	v_mov_b32_e32 v19, v221
	v_mov_b32_e32 v20, v222
	v_mov_b32_e32 v21, v223
	ds_bpermute_b32 v119, v157, v117
	ds_bpermute_b32 v118, v157, v116
	v_mov_b32_e32 v23, v14
	v_mov_b32_e32 v22, v18
	v_mov_b32_e32 v24, v20
	v_mov_b32_e32 v25, v16
	v_pk_add_f32 v[22:23], v[22:23], v[24:25]
	v_add_f32_e32 v14, v19, v21
	v_add_f32_e32 v16, v15, v17
	v_mov_b32_e32 v15, v22
	v_mov_b32_e32 v17, v23
	v_pk_add_f32 v[14:15], v[14:15], v[16:17]
	ds_bpermute_b32 v17, v155, v15
	ds_bpermute_b32 v16, v155, v14
	s_waitcnt lgkmcnt(0)
	v_pk_add_f32 v[120:121], v[14:15], v[16:17]
	v_lshlrev_b64 v[14:15], 7, v[60:61]
	v_lshl_add_u64 v[6:7], v[6:7], 0, v[14:15]
	v_mov_b32_e32 v14, v224
	v_mov_b32_e32 v15, v225
	v_mov_b32_e32 v16, v226
	v_mov_b32_e32 v17, v227
	v_mov_b32_e32 v18, v228
	v_mov_b32_e32 v19, v229
	v_mov_b32_e32 v20, v230
	v_mov_b32_e32 v21, v231
	ds_bpermute_b32 v123, v157, v121
	ds_bpermute_b32 v122, v157, v120
	v_mov_b32_e32 v7, v14
	v_mov_b32_e32 v6, v18
	v_mov_b32_e32 v22, v20
	v_mov_b32_e32 v23, v16
	v_pk_add_f32 v[6:7], v[6:7], v[22:23]
	v_add_f32_e32 v14, v19, v21
	v_add_f32_e32 v16, v15, v17
	v_mov_b32_e32 v15, v6
	v_mov_b32_e32 v17, v7
	v_pk_add_f32 v[6:7], v[14:15], v[16:17]
	ds_bpermute_b32 v15, v155, v7
	ds_bpermute_b32 v14, v155, v6
	s_waitcnt lgkmcnt(0)
	v_pk_add_f32 v[124:125], v[6:7], v[14:15]
	v_lshlrev_b64 v[6:7], 2, v[2:3]
	v_lshlrev_b64 v[2:3], 1, v[2:3]
	v_lshl_add_u64 v[74:75], v[0:1], 0, v[2:3]
	v_lshlrev_b64 v[0:1], 11, v[4:5]
	v_lshl_add_u64 v[0:1], s[44:45], 0, v[0:1]
	v_lshl_add_u64 v[76:77], v[0:1], 0, v[2:3]
	v_lshlrev_b64 v[0:1], 11, v[8:9]
	v_lshl_add_u64 v[0:1], s[44:45], 0, v[0:1]
	v_lshl_add_u64 v[78:79], v[0:1], 0, v[2:3]
	v_lshlrev_b64 v[0:1], 11, v[10:11]
	v_lshl_add_u64 v[0:1], s[44:45], 0, v[0:1]
	v_lshl_add_u64 v[80:81], v[0:1], 0, v[2:3]
	v_lshlrev_b64 v[0:1], 11, v[12:13]
	v_lshl_add_u64 v[0:1], s[44:45], 0, v[0:1]
	v_lshl_add_u64 v[146:147], v[0:1], 0, v[2:3]
	v_lshlrev_b64 v[0:1], 11, v[56:57]
	v_lshl_add_u64 v[0:1], s[44:45], 0, v[0:1]
	v_lshl_add_u64 v[56:57], v[0:1], 0, v[2:3]
	v_lshlrev_b64 v[0:1], 11, v[58:59]
	v_lshl_add_u64 v[0:1], s[44:45], 0, v[0:1]
	v_lshl_add_u64 v[58:59], v[0:1], 0, v[2:3]
	v_lshlrev_b64 v[0:1], 11, v[60:61]
	v_lshl_add_u64 v[0:1], s[44:45], 0, v[0:1]
	v_lshl_add_u64 v[62:63], s[18:19], 0, v[6:7]
	v_lshl_add_u64 v[72:73], s[20:21], 0, v[6:7]
	v_lshl_add_u64 v[148:149], v[0:1], 0, v[2:3]
	global_load_dwordx4 v[36:39], v[62:63], off offset:16
	global_load_dwordx4 v[44:47], v[62:63], off
	global_load_dwordx4 v[32:35], v[72:73], off offset:16
	global_load_dwordx4 v[40:43], v[72:73], off
	global_load_dwordx4 v[28:31], v[74:75], off
	global_load_dwordx4 v[24:27], v[76:77], off
	global_load_dwordx4 v[20:23], v[78:79], off
	global_load_dwordx4 v[16:19], v[80:81], off
	global_load_dwordx4 v[12:15], v[146:147], off
	global_load_dwordx4 v[8:11], v[56:57], off
	global_load_dwordx4 v[4:7], v[58:59], off
	global_load_dwordx4 v[0:3], v[148:149], off
	global_load_dwordx4 v[104:107], v[62:63], off offset:528
	global_load_dwordx4 v[108:111], v[62:63], off offset:512
	global_load_dwordx4 v[96:99], v[72:73], off offset:528
	global_load_dwordx4 v[100:103], v[72:73], off offset:512
	global_load_dwordx4 v[92:95], v[74:75], off offset:256
	global_load_dwordx4 v[88:91], v[76:77], off offset:256
	global_load_dwordx4 v[84:87], v[78:79], off offset:256
	s_nop 0
	global_load_dwordx4 v[80:83], v[80:81], off offset:256
	s_nop 0
	global_load_dwordx4 v[76:79], v[146:147], off offset:256
	global_load_dwordx4 v[72:75], v[56:57], off offset:256
	global_load_dwordx4 v[60:63], v[58:59], off offset:256
	s_nop 0
	global_load_dwordx4 v[56:59], v[148:149], off offset:256
	ds_bpermute_b32 v127, v157, v125
	ds_bpermute_b32 v126, v157, v124
	s_cbranch_vccnz .LBB0_817
	s_barrier
	s_branch .LBB0_817

.LBB0_1532:
	s_or_b64 exec, exec, s[46:47]
	s_andn2_b64 vcc, exec, s[8:9]
	s_mov_b64 s[8:9], -1
	s_cbranch_vccnz .LBB0_1505
	v_mov_b32_e32 v1, v151
	v_mov_b32_e32 v0, v153
	s_lshl_b32 s8, s36, 8
	s_add_i32 s8, s8, s11
	v_add_u32_e32 v0, s8, v0
	s_waitcnt lgkmcnt(0)
	v_lshlrev_b32_e32 v2, 3, v1
	v_ashrrev_i32_e32 v3, 31, v2
	v_ashrrev_i32_e32 v1, 31, v0
	v_lshl_add_u64 v[6:7], v[2:3], 2, s[76:77]
	v_lshlrev_b64 v[4:5], 7, v[0:1]
	v_lshl_add_u64 v[4:5], v[6:7], 0, v[4:5]
	v_mov_b32_e32 v100, v0
	v_ashrrev_i32_e32 v101, 31, v100
	v_lshlrev_b64 v[100:101], 7, v[100:101]
	v_lshl_add_u64 v[100:101], v[6:7], 0, v[100:101]
	global_load_dwordx4 v[104:107], v[100:101], off offset:16
	global_load_dwordx4 v[108:111], v[100:101], off
	v_add_u32_e32 v100, 0x10, v0
	v_ashrrev_i32_e32 v101, 31, v100
	v_lshlrev_b64 v[100:101], 7, v[100:101]
	v_lshl_add_u64 v[100:101], v[6:7], 0, v[100:101]
	global_load_dwordx4 v[124:127], v[100:101], off offset:16
	global_load_dwordx4 v[180:183], v[100:101], off
	v_add_u32_e32 v100, 0x20, v0
	v_ashrrev_i32_e32 v101, 31, v100
	v_lshlrev_b64 v[100:101], 7, v[100:101]
	v_lshl_add_u64 v[100:101], v[6:7], 0, v[100:101]
	global_load_dwordx4 v[184:187], v[100:101], off offset:16
	global_load_dwordx4 v[188:191], v[100:101], off
	v_add_u32_e32 v100, 0x30, v0
	v_ashrrev_i32_e32 v101, 31, v100
	v_lshlrev_b64 v[100:101], 7, v[100:101]
	v_lshl_add_u64 v[100:101], v[6:7], 0, v[100:101]
	global_load_dwordx4 v[192:195], v[100:101], off offset:16
	global_load_dwordx4 v[196:199], v[100:101], off
	v_add_u32_e32 v100, 0x80, v0
	v_ashrrev_i32_e32 v101, 31, v100
	v_lshlrev_b64 v[100:101], 7, v[100:101]
	v_lshl_add_u64 v[100:101], v[6:7], 0, v[100:101]
	global_load_dwordx4 v[200:203], v[100:101], off offset:16
	global_load_dwordx4 v[204:207], v[100:101], off
	v_add_u32_e32 v100, 0x90, v0
	v_ashrrev_i32_e32 v101, 31, v100
	v_lshlrev_b64 v[100:101], 7, v[100:101]
	v_lshl_add_u64 v[100:101], v[6:7], 0, v[100:101]
	global_load_dwordx4 v[208:211], v[100:101], off offset:16
	global_load_dwordx4 v[212:215], v[100:101], off
	v_add_u32_e32 v100, 0xa0, v0
	v_ashrrev_i32_e32 v101, 31, v100
	v_lshlrev_b64 v[100:101], 7, v[100:101]
	v_lshl_add_u64 v[100:101], v[6:7], 0, v[100:101]
	global_load_dwordx4 v[216:219], v[100:101], off offset:16
	global_load_dwordx4 v[220:223], v[100:101], off
	v_add_u32_e32 v100, 0xb0, v0
	v_ashrrev_i32_e32 v101, 31, v100
	v_lshlrev_b64 v[100:101], 7, v[100:101]
	v_lshl_add_u64 v[100:101], v[6:7], 0, v[100:101]
	global_load_dwordx4 v[224:227], v[100:101], off offset:16
	global_load_dwordx4 v[228:231], v[100:101], off
	s_waitcnt vmcnt(0)
	v_mov_b32_e32 v8, v104
	v_mov_b32_e32 v9, v105
	v_mov_b32_e32 v10, v106
	v_mov_b32_e32 v11, v107
	v_mov_b32_e32 v12, v108
	v_mov_b32_e32 v13, v109
	v_mov_b32_e32 v14, v110
	v_mov_b32_e32 v15, v111
	v_add_u32_e32 v56, 0x90, v0
	v_ashrrev_i32_e32 v57, 31, v56
	v_add_u32_e32 v58, 0xa0, v0
	v_ashrrev_i32_e32 v59, 31, v58
	v_add_u32_e32 v60, 0xb0, v0
	v_ashrrev_i32_e32 v61, 31, v60
	s_lshl_b32 s8, s34, 8
	s_or_b32 s8, s8, s66
	v_add_u32_e32 v2, s8, v2
	v_ashrrev_i32_e32 v3, 31, v2
	s_andn2_b64 vcc, exec, s[4:5]
	v_mov_b32_e32 v5, v8
	v_mov_b32_e32 v4, v12
	v_mov_b32_e32 v16, v14
	v_mov_b32_e32 v17, v10
	v_pk_add_f32 v[4:5], v[4:5], v[16:17]
	v_add_f32_e32 v8, v13, v15
	v_add_f32_e32 v10, v9, v11
	v_mov_b32_e32 v9, v4
	v_mov_b32_e32 v11, v5
	v_pk_add_f32 v[4:5], v[8:9], v[10:11]
	ds_bpermute_b32 v9, v155, v5
	ds_bpermute_b32 v8, v155, v4
	s_waitcnt lgkmcnt(0)
	v_pk_add_f32 v[48:49], v[4:5], v[8:9]
	v_add_u32_e32 v4, 16, v0
	v_ashrrev_i32_e32 v5, 31, v4
	v_lshlrev_b64 v[8:9], 7, v[4:5]
	v_lshl_add_u64 v[12:13], v[6:7], 0, v[8:9]
	v_mov_b32_e32 v8, v124
	v_mov_b32_e32 v9, v125
	v_mov_b32_e32 v10, v126
	v_mov_b32_e32 v11, v127
	s_nop 0
	v_mov_b32_e32 v12, v180
	v_mov_b32_e32 v13, v181
	v_mov_b32_e32 v14, v182
	v_mov_b32_e32 v15, v183
	ds_bpermute_b32 v51, v157, v49
	ds_bpermute_b32 v50, v157, v48
	v_mov_b32_e32 v17, v8
	v_mov_b32_e32 v16, v12
	v_mov_b32_e32 v18, v14
	v_mov_b32_e32 v19, v10
	v_pk_add_f32 v[16:17], v[16:17], v[18:19]
	v_add_f32_e32 v8, v13, v15
	v_add_f32_e32 v10, v9, v11
	v_mov_b32_e32 v9, v16
	v_mov_b32_e32 v11, v17
	v_pk_add_f32 v[8:9], v[8:9], v[10:11]
	ds_bpermute_b32 v11, v155, v9
	ds_bpermute_b32 v10, v155, v8
	s_waitcnt lgkmcnt(0)
	v_pk_add_f32 v[52:53], v[8:9], v[10:11]
	v_add_u32_e32 v8, 32, v0
	v_ashrrev_i32_e32 v9, 31, v8
	v_lshlrev_b64 v[10:11], 7, v[8:9]
	v_lshl_add_u64 v[14:15], v[6:7], 0, v[10:11]
	v_mov_b32_e32 v10, v184
	v_mov_b32_e32 v11, v185
	v_mov_b32_e32 v12, v186
	v_mov_b32_e32 v13, v187
	s_nop 0
	v_mov_b32_e32 v14, v188
	v_mov_b32_e32 v15, v189
	v_mov_b32_e32 v16, v190
	v_mov_b32_e32 v17, v191
	ds_bpermute_b32 v55, v157, v53
	ds_bpermute_b32 v54, v157, v52
	v_mov_b32_e32 v19, v10
	v_mov_b32_e32 v18, v14
	v_mov_b32_e32 v20, v16
	v_mov_b32_e32 v21, v12
	v_pk_add_f32 v[18:19], v[18:19], v[20:21]
	v_add_f32_e32 v10, v15, v17
	v_add_f32_e32 v12, v11, v13
	v_mov_b32_e32 v11, v18
	v_mov_b32_e32 v13, v19
	v_pk_add_f32 v[10:11], v[10:11], v[12:13]
	ds_bpermute_b32 v13, v155, v11
	ds_bpermute_b32 v12, v155, v10
	s_waitcnt lgkmcnt(0)
	v_pk_add_f32 v[64:65], v[10:11], v[12:13]
	v_add_u32_e32 v10, 48, v0
	v_ashrrev_i32_e32 v11, 31, v10
	v_lshlrev_b64 v[12:13], 7, v[10:11]
	v_lshl_add_u64 v[16:17], v[6:7], 0, v[12:13]
	v_mov_b32_e32 v12, v192
	v_mov_b32_e32 v13, v193
	v_mov_b32_e32 v14, v194
	v_mov_b32_e32 v15, v195
	s_nop 0
	v_mov_b32_e32 v16, v196
	v_mov_b32_e32 v17, v197
	v_mov_b32_e32 v18, v198
	v_mov_b32_e32 v19, v199
	ds_bpermute_b32 v67, v157, v65
	ds_bpermute_b32 v66, v157, v64
	v_mov_b32_e32 v21, v12
	v_mov_b32_e32 v20, v16
	v_mov_b32_e32 v22, v18
	v_mov_b32_e32 v23, v14
	v_pk_add_f32 v[20:21], v[20:21], v[22:23]
	v_add_f32_e32 v12, v17, v19
	v_add_f32_e32 v14, v13, v15
	v_mov_b32_e32 v13, v20
	v_mov_b32_e32 v15, v21
	v_pk_add_f32 v[12:13], v[12:13], v[14:15]
	ds_bpermute_b32 v15, v155, v13
	ds_bpermute_b32 v14, v155, v12
	s_waitcnt lgkmcnt(0)
	v_pk_add_f32 v[68:69], v[12:13], v[14:15]
	v_add_u32_e32 v12, 0x80, v0
	v_ashrrev_i32_e32 v13, 31, v12
	v_lshlrev_b64 v[14:15], 7, v[12:13]
	v_lshl_add_u64 v[18:19], v[6:7], 0, v[14:15]
	v_mov_b32_e32 v14, v200
	v_mov_b32_e32 v15, v201
	v_mov_b32_e32 v16, v202
	v_mov_b32_e32 v17, v203
	s_nop 0
	v_mov_b32_e32 v18, v204
	v_mov_b32_e32 v19, v205
	v_mov_b32_e32 v20, v206
	v_mov_b32_e32 v21, v207
	v_lshlrev_b64 v[0:1], 11, v[0:1]
	v_lshl_add_u64 v[0:1], s[44:45], 0, v[0:1]
	ds_bpermute_b32 v71, v157, v69
	ds_bpermute_b32 v70, v157, v68
	v_mov_b32_e32 v23, v14
	v_mov_b32_e32 v22, v18
	v_mov_b32_e32 v24, v20
	v_mov_b32_e32 v25, v16
	v_pk_add_f32 v[22:23], v[22:23], v[24:25]
	v_add_f32_e32 v14, v19, v21
	v_add_f32_e32 v16, v15, v17
	v_mov_b32_e32 v15, v22
	v_mov_b32_e32 v17, v23
	v_pk_add_f32 v[14:15], v[14:15], v[16:17]
	ds_bpermute_b32 v17, v155, v15
	ds_bpermute_b32 v16, v155, v14
	s_waitcnt lgkmcnt(0)
	v_pk_add_f32 v[112:113], v[14:15], v[16:17]
	v_lshlrev_b64 v[14:15], 7, v[56:57]
	v_lshl_add_u64 v[18:19], v[6:7], 0, v[14:15]
	v_mov_b32_e32 v14, v208
	v_mov_b32_e32 v15, v209
	v_mov_b32_e32 v16, v210
	v_mov_b32_e32 v17, v211
	s_nop 0
	v_mov_b32_e32 v18, v212
	v_mov_b32_e32 v19, v213
	v_mov_b32_e32 v20, v214
	v_mov_b32_e32 v21, v215
	ds_bpermute_b32 v115, v157, v113
	ds_bpermute_b32 v114, v157, v112
	v_mov_b32_e32 v23, v14
	v_mov_b32_e32 v22, v18
	v_mov_b32_e32 v24, v20
	v_mov_b32_e32 v25, v16
	v_pk_add_f32 v[22:23], v[22:23], v[24:25]
	v_add_f32_e32 v14, v19, v21
	v_add_f32_e32 v16, v15, v17
	v_mov_b32_e32 v15, v22
	v_mov_b32_e32 v17, v23
	v_pk_add_f32 v[14:15], v[14:15], v[16:17]
	ds_bpermute_b32 v17, v155, v15
	ds_bpermute_b32 v16, v155, v14
	s_waitcnt lgkmcnt(0)
	v_pk_add_f32 v[116:117], v[14:15], v[16:17]
	v_lshlrev_b64 v[14:15], 7, v[58:59]
	v_lshl_add_u64 v[18:19], v[6:7], 0, v[14:15]
	v_mov_b32_e32 v14, v216
	v_mov_b32_e32 v15, v217
	v_mov_b32_e32 v16, v218
	v_mov_b32_e32 v17, v219
	s_nop 0
	v_mov_b32_e32 v18, v220
	v_mov_b32_e32 v19, v221
	v_mov_b32_e32 v20, v222
	v_mov_b32_e32 v21, v223
	ds_bpermute_b32 v119, v157, v117
	ds_bpermute_b32 v118, v157, v116
	v_mov_b32_e32 v23, v14
	v_mov_b32_e32 v22, v18
	v_mov_b32_e32 v24, v20
	v_mov_b32_e32 v25, v16
	v_pk_add_f32 v[22:23], v[22:23], v[24:25]
	v_add_f32_e32 v14, v19, v21
	v_add_f32_e32 v16, v15, v17
	v_mov_b32_e32 v15, v22
	v_mov_b32_e32 v17, v23
	v_pk_add_f32 v[14:15], v[14:15], v[16:17]
	ds_bpermute_b32 v17, v155, v15
	ds_bpermute_b32 v16, v155, v14
	s_waitcnt lgkmcnt(0)
	v_pk_add_f32 v[120:121], v[14:15], v[16:17]
	v_lshlrev_b64 v[14:15], 7, v[60:61]
	v_lshl_add_u64 v[6:7], v[6:7], 0, v[14:15]
	v_mov_b32_e32 v14, v224
	v_mov_b32_e32 v15, v225
	v_mov_b32_e32 v16, v226
	v_mov_b32_e32 v17, v227
	v_mov_b32_e32 v18, v228
	v_mov_b32_e32 v19, v229
	v_mov_b32_e32 v20, v230
	v_mov_b32_e32 v21, v231
	ds_bpermute_b32 v123, v157, v121
	ds_bpermute_b32 v122, v157, v120
	v_mov_b32_e32 v7, v14
	v_mov_b32_e32 v6, v18
	v_mov_b32_e32 v22, v20
	v_mov_b32_e32 v23, v16
	v_pk_add_f32 v[6:7], v[6:7], v[22:23]
	v_add_f32_e32 v14, v19, v21
	v_add_f32_e32 v16, v15, v17
	v_mov_b32_e32 v15, v6
	v_mov_b32_e32 v17, v7
	v_pk_add_f32 v[6:7], v[14:15], v[16:17]
	ds_bpermute_b32 v15, v155, v7
	ds_bpermute_b32 v14, v155, v6
	s_waitcnt lgkmcnt(0)
	v_pk_add_f32 v[124:125], v[6:7], v[14:15]
	v_lshlrev_b64 v[6:7], 2, v[2:3]
	v_lshlrev_b64 v[2:3], 1, v[2:3]
	v_lshl_add_u64 v[74:75], v[0:1], 0, v[2:3]
	v_lshlrev_b64 v[0:1], 11, v[4:5]
	v_lshl_add_u64 v[0:1], s[44:45], 0, v[0:1]
	v_lshl_add_u64 v[76:77], v[0:1], 0, v[2:3]
	v_lshlrev_b64 v[0:1], 11, v[8:9]
	v_lshl_add_u64 v[0:1], s[44:45], 0, v[0:1]
	v_lshl_add_u64 v[78:79], v[0:1], 0, v[2:3]
	v_lshlrev_b64 v[0:1], 11, v[10:11]
	v_lshl_add_u64 v[0:1], s[44:45], 0, v[0:1]
	v_lshl_add_u64 v[80:81], v[0:1], 0, v[2:3]
	v_lshlrev_b64 v[0:1], 11, v[12:13]
	v_lshl_add_u64 v[0:1], s[44:45], 0, v[0:1]
	v_lshl_add_u64 v[146:147], v[0:1], 0, v[2:3]
	v_lshlrev_b64 v[0:1], 11, v[56:57]
	v_lshl_add_u64 v[0:1], s[44:45], 0, v[0:1]
	v_lshl_add_u64 v[56:57], v[0:1], 0, v[2:3]
	v_lshlrev_b64 v[0:1], 11, v[58:59]
	v_lshl_add_u64 v[0:1], s[44:45], 0, v[0:1]
	v_lshl_add_u64 v[58:59], v[0:1], 0, v[2:3]
	v_lshlrev_b64 v[0:1], 11, v[60:61]
	v_lshl_add_u64 v[0:1], s[44:45], 0, v[0:1]
	v_lshl_add_u64 v[62:63], s[28:29], 0, v[6:7]
	v_lshl_add_u64 v[72:73], s[30:31], 0, v[6:7]
	v_lshl_add_u64 v[148:149], v[0:1], 0, v[2:3]
	global_load_dwordx4 v[36:39], v[62:63], off offset:16
	global_load_dwordx4 v[44:47], v[62:63], off
	global_load_dwordx4 v[32:35], v[72:73], off offset:16
	global_load_dwordx4 v[40:43], v[72:73], off
	global_load_dwordx4 v[28:31], v[74:75], off
	global_load_dwordx4 v[24:27], v[76:77], off
	global_load_dwordx4 v[20:23], v[78:79], off
	global_load_dwordx4 v[16:19], v[80:81], off
	global_load_dwordx4 v[12:15], v[146:147], off
	global_load_dwordx4 v[8:11], v[56:57], off
	global_load_dwordx4 v[4:7], v[58:59], off
	global_load_dwordx4 v[0:3], v[148:149], off
	global_load_dwordx4 v[104:107], v[62:63], off offset:528
	global_load_dwordx4 v[108:111], v[62:63], off offset:512
	global_load_dwordx4 v[96:99], v[72:73], off offset:528
	global_load_dwordx4 v[100:103], v[72:73], off offset:512
	global_load_dwordx4 v[92:95], v[74:75], off offset:256
	global_load_dwordx4 v[88:91], v[76:77], off offset:256
	global_load_dwordx4 v[84:87], v[78:79], off offset:256
	s_nop 0
	global_load_dwordx4 v[80:83], v[80:81], off offset:256
	s_nop 0
	global_load_dwordx4 v[76:79], v[146:147], off offset:256
	global_load_dwordx4 v[72:75], v[56:57], off offset:256
	global_load_dwordx4 v[60:63], v[58:59], off offset:256
	s_nop 0
	global_load_dwordx4 v[56:59], v[148:149], off offset:256
	ds_bpermute_b32 v127, v157, v125
	ds_bpermute_b32 v126, v157, v124
	s_cbranch_vccnz .LBB0_1504
	s_barrier
	s_branch .LBB0_1504

.LBB0_1709:
	s_or_b64 exec, exec, s[46:47]
	s_and_b64 vcc, exec, s[10:11]
	s_mov_b64 s[10:11], -1
	s_cbranch_vccnz .LBB0_1678
	v_mov_b32_e32 v0, v153
	v_mov_b32_e32 v1, v151
	s_lshl_b32 s10, s78, 8
	s_add_i32 s10, s10, s15
	v_add_u32_e32 v0, s10, v0
	s_waitcnt lgkmcnt(0)
	v_lshlrev_b32_e32 v2, 3, v1
	v_ashrrev_i32_e32 v3, 31, v2
	v_ashrrev_i32_e32 v1, 31, v0
	v_lshl_add_u64 v[6:7], v[2:3], 2, s[62:63]
	v_lshlrev_b64 v[4:5], 7, v[0:1]
	v_lshl_add_u64 v[4:5], v[6:7], 0, v[4:5]
	v_mov_b32_e32 v100, v0
	v_ashrrev_i32_e32 v101, 31, v100
	v_lshlrev_b64 v[100:101], 7, v[100:101]
	v_lshl_add_u64 v[100:101], v[6:7], 0, v[100:101]
	global_load_dwordx4 v[104:107], v[100:101], off offset:16
	global_load_dwordx4 v[108:111], v[100:101], off
	v_add_u32_e32 v100, 0x10, v0
	v_ashrrev_i32_e32 v101, 31, v100
	v_lshlrev_b64 v[100:101], 7, v[100:101]
	v_lshl_add_u64 v[100:101], v[6:7], 0, v[100:101]
	global_load_dwordx4 v[124:127], v[100:101], off offset:16
	global_load_dwordx4 v[180:183], v[100:101], off
	v_add_u32_e32 v100, 0x20, v0
	v_ashrrev_i32_e32 v101, 31, v100
	v_lshlrev_b64 v[100:101], 7, v[100:101]
	v_lshl_add_u64 v[100:101], v[6:7], 0, v[100:101]
	global_load_dwordx4 v[184:187], v[100:101], off offset:16
	global_load_dwordx4 v[188:191], v[100:101], off
	v_add_u32_e32 v100, 0x30, v0
	v_ashrrev_i32_e32 v101, 31, v100
	v_lshlrev_b64 v[100:101], 7, v[100:101]
	v_lshl_add_u64 v[100:101], v[6:7], 0, v[100:101]
	global_load_dwordx4 v[192:195], v[100:101], off offset:16
	global_load_dwordx4 v[196:199], v[100:101], off
	v_add_u32_e32 v100, 0x80, v0
	v_ashrrev_i32_e32 v101, 31, v100
	v_lshlrev_b64 v[100:101], 7, v[100:101]
	v_lshl_add_u64 v[100:101], v[6:7], 0, v[100:101]
	global_load_dwordx4 v[200:203], v[100:101], off offset:16
	global_load_dwordx4 v[204:207], v[100:101], off
	v_add_u32_e32 v100, 0x90, v0
	v_ashrrev_i32_e32 v101, 31, v100
	v_lshlrev_b64 v[100:101], 7, v[100:101]
	v_lshl_add_u64 v[100:101], v[6:7], 0, v[100:101]
	global_load_dwordx4 v[208:211], v[100:101], off offset:16
	global_load_dwordx4 v[212:215], v[100:101], off
	v_add_u32_e32 v100, 0xa0, v0
	v_ashrrev_i32_e32 v101, 31, v100
	v_lshlrev_b64 v[100:101], 7, v[100:101]
	v_lshl_add_u64 v[100:101], v[6:7], 0, v[100:101]
	global_load_dwordx4 v[216:219], v[100:101], off offset:16
	global_load_dwordx4 v[220:223], v[100:101], off
	v_add_u32_e32 v100, 0xb0, v0
	v_ashrrev_i32_e32 v101, 31, v100
	v_lshlrev_b64 v[100:101], 7, v[100:101]
	v_lshl_add_u64 v[100:101], v[6:7], 0, v[100:101]
	global_load_dwordx4 v[224:227], v[100:101], off offset:16
	global_load_dwordx4 v[228:231], v[100:101], off
	s_waitcnt vmcnt(0)
	v_mov_b32_e32 v8, v104
	v_mov_b32_e32 v9, v105
	v_mov_b32_e32 v10, v106
	v_mov_b32_e32 v11, v107
	v_mov_b32_e32 v12, v108
	v_mov_b32_e32 v13, v109
	v_mov_b32_e32 v14, v110
	v_mov_b32_e32 v15, v111
	v_add_u32_e32 v56, 0x90, v0
	v_ashrrev_i32_e32 v57, 31, v56
	v_add_u32_e32 v58, 0xa0, v0
	v_ashrrev_i32_e32 v59, 31, v58
	v_add_u32_e32 v60, 0xb0, v0
	v_ashrrev_i32_e32 v61, 31, v60
	s_lshl_b32 s10, s73, 8
	s_or_b32 s10, s10, s66
	v_add_u32_e32 v2, s10, v2
	v_ashrrev_i32_e32 v3, 31, v2
	v_readlane_b32 s10, v255, 48
	v_readlane_b32 s11, v255, 49
	s_andn2_b64 vcc, exec, s[6:7]
	v_mov_b32_e32 v5, v8
	v_mov_b32_e32 v4, v12
	v_mov_b32_e32 v16, v14
	v_mov_b32_e32 v17, v10
	v_pk_add_f32 v[4:5], v[4:5], v[16:17]
	v_add_f32_e32 v8, v13, v15
	v_add_f32_e32 v10, v9, v11
	v_mov_b32_e32 v9, v4
	v_mov_b32_e32 v11, v5
	v_pk_add_f32 v[4:5], v[8:9], v[10:11]
	ds_bpermute_b32 v9, v155, v5
	ds_bpermute_b32 v8, v155, v4
	s_waitcnt lgkmcnt(0)
	v_pk_add_f32 v[48:49], v[4:5], v[8:9]
	v_add_u32_e32 v4, 16, v0
	v_ashrrev_i32_e32 v5, 31, v4
	v_lshlrev_b64 v[8:9], 7, v[4:5]
	v_lshl_add_u64 v[12:13], v[6:7], 0, v[8:9]
	v_mov_b32_e32 v8, v124
	v_mov_b32_e32 v9, v125
	v_mov_b32_e32 v10, v126
	v_mov_b32_e32 v11, v127
	s_nop 0
	v_mov_b32_e32 v12, v180
	v_mov_b32_e32 v13, v181
	v_mov_b32_e32 v14, v182
	v_mov_b32_e32 v15, v183
	ds_bpermute_b32 v51, v157, v49
	ds_bpermute_b32 v50, v157, v48
	v_mov_b32_e32 v17, v8
	v_mov_b32_e32 v16, v12
	v_mov_b32_e32 v18, v14
	v_mov_b32_e32 v19, v10
	v_pk_add_f32 v[16:17], v[16:17], v[18:19]
	v_add_f32_e32 v8, v13, v15
	v_add_f32_e32 v10, v9, v11
	v_mov_b32_e32 v9, v16
	v_mov_b32_e32 v11, v17
	v_pk_add_f32 v[8:9], v[8:9], v[10:11]
	ds_bpermute_b32 v11, v155, v9
	ds_bpermute_b32 v10, v155, v8
	s_waitcnt lgkmcnt(0)
	v_pk_add_f32 v[52:53], v[8:9], v[10:11]
	v_add_u32_e32 v8, 32, v0
	v_ashrrev_i32_e32 v9, 31, v8
	v_lshlrev_b64 v[10:11], 7, v[8:9]
	v_lshl_add_u64 v[14:15], v[6:7], 0, v[10:11]
	v_mov_b32_e32 v10, v184
	v_mov_b32_e32 v11, v185
	v_mov_b32_e32 v12, v186
	v_mov_b32_e32 v13, v187
	s_nop 0
	v_mov_b32_e32 v14, v188
	v_mov_b32_e32 v15, v189
	v_mov_b32_e32 v16, v190
	v_mov_b32_e32 v17, v191
	ds_bpermute_b32 v55, v157, v53
	ds_bpermute_b32 v54, v157, v52
	v_mov_b32_e32 v19, v10
	v_mov_b32_e32 v18, v14
	v_mov_b32_e32 v20, v16
	v_mov_b32_e32 v21, v12
	v_pk_add_f32 v[18:19], v[18:19], v[20:21]
	v_add_f32_e32 v10, v15, v17
	v_add_f32_e32 v12, v11, v13
	v_mov_b32_e32 v11, v18
	v_mov_b32_e32 v13, v19
	v_pk_add_f32 v[10:11], v[10:11], v[12:13]
	ds_bpermute_b32 v13, v155, v11
	ds_bpermute_b32 v12, v155, v10
	s_waitcnt lgkmcnt(0)
	v_pk_add_f32 v[64:65], v[10:11], v[12:13]
	v_add_u32_e32 v10, 48, v0
	v_ashrrev_i32_e32 v11, 31, v10
	v_lshlrev_b64 v[12:13], 7, v[10:11]
	v_lshl_add_u64 v[16:17], v[6:7], 0, v[12:13]
	v_mov_b32_e32 v12, v192
	v_mov_b32_e32 v13, v193
	v_mov_b32_e32 v14, v194
	v_mov_b32_e32 v15, v195
	s_nop 0
	v_mov_b32_e32 v16, v196
	v_mov_b32_e32 v17, v197
	v_mov_b32_e32 v18, v198
	v_mov_b32_e32 v19, v199
	ds_bpermute_b32 v67, v157, v65
	ds_bpermute_b32 v66, v157, v64
	v_mov_b32_e32 v21, v12
	v_mov_b32_e32 v20, v16
	v_mov_b32_e32 v22, v18
	v_mov_b32_e32 v23, v14
	v_pk_add_f32 v[20:21], v[20:21], v[22:23]
	v_add_f32_e32 v12, v17, v19
	v_add_f32_e32 v14, v13, v15
	v_mov_b32_e32 v13, v20
	v_mov_b32_e32 v15, v21
	v_pk_add_f32 v[12:13], v[12:13], v[14:15]
	ds_bpermute_b32 v15, v155, v13
	ds_bpermute_b32 v14, v155, v12
	s_waitcnt lgkmcnt(0)
	v_pk_add_f32 v[68:69], v[12:13], v[14:15]
	v_add_u32_e32 v12, 0x80, v0
	v_ashrrev_i32_e32 v13, 31, v12
	v_lshlrev_b64 v[14:15], 7, v[12:13]
	v_lshl_add_u64 v[18:19], v[6:7], 0, v[14:15]
	v_mov_b32_e32 v14, v200
	v_mov_b32_e32 v15, v201
	v_mov_b32_e32 v16, v202
	v_mov_b32_e32 v17, v203
	s_nop 0
	v_mov_b32_e32 v18, v204
	v_mov_b32_e32 v19, v205
	v_mov_b32_e32 v20, v206
	v_mov_b32_e32 v21, v207
	v_lshlrev_b64 v[0:1], 11, v[0:1]
	v_lshl_add_u64 v[0:1], s[44:45], 0, v[0:1]
	ds_bpermute_b32 v71, v157, v69
	ds_bpermute_b32 v70, v157, v68
	v_mov_b32_e32 v23, v14
	v_mov_b32_e32 v22, v18
	v_mov_b32_e32 v24, v20
	v_mov_b32_e32 v25, v16
	v_pk_add_f32 v[22:23], v[22:23], v[24:25]
	v_add_f32_e32 v14, v19, v21
	v_add_f32_e32 v16, v15, v17
	v_mov_b32_e32 v15, v22
	v_mov_b32_e32 v17, v23
	v_pk_add_f32 v[14:15], v[14:15], v[16:17]
	ds_bpermute_b32 v17, v155, v15
	ds_bpermute_b32 v16, v155, v14
	s_waitcnt lgkmcnt(0)
	v_pk_add_f32 v[112:113], v[14:15], v[16:17]
	v_lshlrev_b64 v[14:15], 7, v[56:57]
	v_lshl_add_u64 v[18:19], v[6:7], 0, v[14:15]
	v_mov_b32_e32 v14, v208
	v_mov_b32_e32 v15, v209
	v_mov_b32_e32 v16, v210
	v_mov_b32_e32 v17, v211
	s_nop 0
	v_mov_b32_e32 v18, v212
	v_mov_b32_e32 v19, v213
	v_mov_b32_e32 v20, v214
	v_mov_b32_e32 v21, v215
	ds_bpermute_b32 v115, v157, v113
	ds_bpermute_b32 v114, v157, v112
	v_mov_b32_e32 v23, v14
	v_mov_b32_e32 v22, v18
	v_mov_b32_e32 v24, v20
	v_mov_b32_e32 v25, v16
	v_pk_add_f32 v[22:23], v[22:23], v[24:25]
	v_add_f32_e32 v14, v19, v21
	v_add_f32_e32 v16, v15, v17
	v_mov_b32_e32 v15, v22
	v_mov_b32_e32 v17, v23
	v_pk_add_f32 v[14:15], v[14:15], v[16:17]
	ds_bpermute_b32 v17, v155, v15
	ds_bpermute_b32 v16, v155, v14
	s_waitcnt lgkmcnt(0)
	v_pk_add_f32 v[116:117], v[14:15], v[16:17]
	v_lshlrev_b64 v[14:15], 7, v[58:59]
	v_lshl_add_u64 v[18:19], v[6:7], 0, v[14:15]
	v_mov_b32_e32 v14, v216
	v_mov_b32_e32 v15, v217
	v_mov_b32_e32 v16, v218
	v_mov_b32_e32 v17, v219
	s_nop 0
	v_mov_b32_e32 v18, v220
	v_mov_b32_e32 v19, v221
	v_mov_b32_e32 v20, v222
	v_mov_b32_e32 v21, v223
	ds_bpermute_b32 v119, v157, v117
	ds_bpermute_b32 v118, v157, v116
	v_mov_b32_e32 v23, v14
	v_mov_b32_e32 v22, v18
	v_mov_b32_e32 v24, v20
	v_mov_b32_e32 v25, v16
	v_pk_add_f32 v[22:23], v[22:23], v[24:25]
	v_add_f32_e32 v14, v19, v21
	v_add_f32_e32 v16, v15, v17
	v_mov_b32_e32 v15, v22
	v_mov_b32_e32 v17, v23
	v_pk_add_f32 v[14:15], v[14:15], v[16:17]
	ds_bpermute_b32 v17, v155, v15
	ds_bpermute_b32 v16, v155, v14
	s_waitcnt lgkmcnt(0)
	v_pk_add_f32 v[120:121], v[14:15], v[16:17]
	v_lshlrev_b64 v[14:15], 7, v[60:61]
	v_lshl_add_u64 v[6:7], v[6:7], 0, v[14:15]
	v_mov_b32_e32 v14, v224
	v_mov_b32_e32 v15, v225
	v_mov_b32_e32 v16, v226
	v_mov_b32_e32 v17, v227
	v_mov_b32_e32 v18, v228
	v_mov_b32_e32 v19, v229
	v_mov_b32_e32 v20, v230
	v_mov_b32_e32 v21, v231
	ds_bpermute_b32 v123, v157, v121
	ds_bpermute_b32 v122, v157, v120
	v_mov_b32_e32 v7, v14
	v_mov_b32_e32 v6, v18
	v_mov_b32_e32 v22, v20
	v_mov_b32_e32 v23, v16
	v_pk_add_f32 v[6:7], v[6:7], v[22:23]
	v_add_f32_e32 v14, v19, v21
	v_add_f32_e32 v16, v15, v17
	v_mov_b32_e32 v15, v6
	v_mov_b32_e32 v17, v7
	v_pk_add_f32 v[6:7], v[14:15], v[16:17]
	ds_bpermute_b32 v15, v155, v7
	ds_bpermute_b32 v14, v155, v6
	s_waitcnt lgkmcnt(0)
	v_pk_add_f32 v[124:125], v[6:7], v[14:15]
	v_lshlrev_b64 v[6:7], 2, v[2:3]
	v_lshlrev_b64 v[2:3], 1, v[2:3]
	v_lshl_add_u64 v[74:75], v[0:1], 0, v[2:3]
	v_lshlrev_b64 v[0:1], 11, v[4:5]
	v_lshl_add_u64 v[0:1], s[44:45], 0, v[0:1]
	v_lshl_add_u64 v[76:77], v[0:1], 0, v[2:3]
	v_lshlrev_b64 v[0:1], 11, v[8:9]
	v_lshl_add_u64 v[0:1], s[44:45], 0, v[0:1]
	v_lshl_add_u64 v[78:79], v[0:1], 0, v[2:3]
	v_lshlrev_b64 v[0:1], 11, v[10:11]
	v_lshl_add_u64 v[0:1], s[44:45], 0, v[0:1]
	v_lshl_add_u64 v[80:81], v[0:1], 0, v[2:3]
	v_lshlrev_b64 v[0:1], 11, v[12:13]
	v_lshl_add_u64 v[0:1], s[44:45], 0, v[0:1]
	v_lshl_add_u64 v[146:147], v[0:1], 0, v[2:3]
	v_lshlrev_b64 v[0:1], 11, v[56:57]
	v_lshl_add_u64 v[0:1], s[44:45], 0, v[0:1]
	v_lshl_add_u64 v[56:57], v[0:1], 0, v[2:3]
	v_lshlrev_b64 v[0:1], 11, v[58:59]
	v_lshl_add_u64 v[0:1], s[44:45], 0, v[0:1]
	v_lshl_add_u64 v[58:59], v[0:1], 0, v[2:3]
	v_lshlrev_b64 v[0:1], 11, v[60:61]
	v_lshl_add_u64 v[0:1], s[44:45], 0, v[0:1]
	v_lshl_add_u64 v[62:63], s[10:11], 0, v[6:7]
	v_lshl_add_u64 v[72:73], s[0:1], 0, v[6:7]
	v_lshl_add_u64 v[148:149], v[0:1], 0, v[2:3]
	global_load_dwordx4 v[36:39], v[62:63], off offset:16
	global_load_dwordx4 v[44:47], v[62:63], off
	global_load_dwordx4 v[32:35], v[72:73], off offset:16
	global_load_dwordx4 v[40:43], v[72:73], off
	global_load_dwordx4 v[28:31], v[74:75], off
	global_load_dwordx4 v[24:27], v[76:77], off
	global_load_dwordx4 v[20:23], v[78:79], off
	global_load_dwordx4 v[16:19], v[80:81], off
	global_load_dwordx4 v[12:15], v[146:147], off
	global_load_dwordx4 v[8:11], v[56:57], off
	global_load_dwordx4 v[4:7], v[58:59], off
	global_load_dwordx4 v[0:3], v[148:149], off
	global_load_dwordx4 v[104:107], v[62:63], off offset:528
	global_load_dwordx4 v[108:111], v[62:63], off offset:512
	global_load_dwordx4 v[96:99], v[72:73], off offset:528
	global_load_dwordx4 v[100:103], v[72:73], off offset:512
	global_load_dwordx4 v[92:95], v[74:75], off offset:256
	global_load_dwordx4 v[88:91], v[76:77], off offset:256
	global_load_dwordx4 v[84:87], v[78:79], off offset:256
	s_nop 0
	global_load_dwordx4 v[80:83], v[80:81], off offset:256
	s_nop 0
	global_load_dwordx4 v[76:79], v[146:147], off offset:256
	global_load_dwordx4 v[72:75], v[56:57], off offset:256
	global_load_dwordx4 v[60:63], v[58:59], off offset:256
	s_nop 0
	global_load_dwordx4 v[56:59], v[148:149], off offset:256
	ds_bpermute_b32 v127, v157, v125
	ds_bpermute_b32 v126, v157, v124
	s_cbranch_vccnz .LBB0_1677
	s_barrier
	s_branch .LBB0_1677

.LBB0_2393:
	s_or_b64 exec, exec, s[46:47]
	s_andn2_b64 vcc, exec, s[10:11]
	s_mov_b64 s[10:11], -1
	s_cbranch_vccnz .LBB0_2366
	v_mov_b32_e32 v0, v153
	v_mov_b32_e32 v1, v151
	s_lshl_b32 s10, s60, 8
	s_add_i32 s10, s10, s13
	v_add_u32_e32 v0, s10, v0
	s_waitcnt lgkmcnt(0)
	v_lshlrev_b32_e32 v2, 3, v1
	v_ashrrev_i32_e32 v3, 31, v2
	v_ashrrev_i32_e32 v1, 31, v0
	v_lshl_add_u64 v[6:7], v[2:3], 2, s[76:77]
	v_lshlrev_b64 v[4:5], 7, v[0:1]
	v_lshl_add_u64 v[4:5], v[6:7], 0, v[4:5]
	v_mov_b32_e32 v100, v0
	v_ashrrev_i32_e32 v101, 31, v100
	v_lshlrev_b64 v[100:101], 7, v[100:101]
	v_lshl_add_u64 v[100:101], v[6:7], 0, v[100:101]
	global_load_dwordx4 v[104:107], v[100:101], off offset:16
	global_load_dwordx4 v[108:111], v[100:101], off
	v_add_u32_e32 v100, 0x10, v0
	v_ashrrev_i32_e32 v101, 31, v100
	v_lshlrev_b64 v[100:101], 7, v[100:101]
	v_lshl_add_u64 v[100:101], v[6:7], 0, v[100:101]
	global_load_dwordx4 v[124:127], v[100:101], off offset:16
	global_load_dwordx4 v[180:183], v[100:101], off
	v_add_u32_e32 v100, 0x20, v0
	v_ashrrev_i32_e32 v101, 31, v100
	v_lshlrev_b64 v[100:101], 7, v[100:101]
	v_lshl_add_u64 v[100:101], v[6:7], 0, v[100:101]
	global_load_dwordx4 v[184:187], v[100:101], off offset:16
	global_load_dwordx4 v[188:191], v[100:101], off
	v_add_u32_e32 v100, 0x30, v0
	v_ashrrev_i32_e32 v101, 31, v100
	v_lshlrev_b64 v[100:101], 7, v[100:101]
	v_lshl_add_u64 v[100:101], v[6:7], 0, v[100:101]
	global_load_dwordx4 v[192:195], v[100:101], off offset:16
	global_load_dwordx4 v[196:199], v[100:101], off
	v_add_u32_e32 v100, 0x80, v0
	v_ashrrev_i32_e32 v101, 31, v100
	v_lshlrev_b64 v[100:101], 7, v[100:101]
	v_lshl_add_u64 v[100:101], v[6:7], 0, v[100:101]
	global_load_dwordx4 v[200:203], v[100:101], off offset:16
	global_load_dwordx4 v[204:207], v[100:101], off
	v_add_u32_e32 v100, 0x90, v0
	v_ashrrev_i32_e32 v101, 31, v100
	v_lshlrev_b64 v[100:101], 7, v[100:101]
	v_lshl_add_u64 v[100:101], v[6:7], 0, v[100:101]
	global_load_dwordx4 v[208:211], v[100:101], off offset:16
	global_load_dwordx4 v[212:215], v[100:101], off
	v_add_u32_e32 v100, 0xa0, v0
	v_ashrrev_i32_e32 v101, 31, v100
	v_lshlrev_b64 v[100:101], 7, v[100:101]
	v_lshl_add_u64 v[100:101], v[6:7], 0, v[100:101]
	global_load_dwordx4 v[216:219], v[100:101], off offset:16
	global_load_dwordx4 v[220:223], v[100:101], off
	v_add_u32_e32 v100, 0xb0, v0
	v_ashrrev_i32_e32 v101, 31, v100
	v_lshlrev_b64 v[100:101], 7, v[100:101]
	v_lshl_add_u64 v[100:101], v[6:7], 0, v[100:101]
	global_load_dwordx4 v[224:227], v[100:101], off offset:16
	global_load_dwordx4 v[228:231], v[100:101], off
	s_waitcnt vmcnt(0)
	v_mov_b32_e32 v8, v104
	v_mov_b32_e32 v9, v105
	v_mov_b32_e32 v10, v106
	v_mov_b32_e32 v11, v107
	v_mov_b32_e32 v12, v108
	v_mov_b32_e32 v13, v109
	v_mov_b32_e32 v14, v110
	v_mov_b32_e32 v15, v111
	v_add_u32_e32 v56, 0x90, v0
	v_ashrrev_i32_e32 v57, 31, v56
	v_add_u32_e32 v58, 0xa0, v0
	v_ashrrev_i32_e32 v59, 31, v58
	v_add_u32_e32 v60, 0xb0, v0
	v_ashrrev_i32_e32 v61, 31, v60
	s_lshl_b32 s10, s36, 8
	s_or_b32 s10, s10, s66
	v_add_u32_e32 v2, s10, v2
	v_ashrrev_i32_e32 v3, 31, v2
	v_readlane_b32 s10, v255, 48
	v_readlane_b32 s11, v255, 49
	s_andn2_b64 vcc, exec, s[6:7]
	v_mov_b32_e32 v5, v8
	v_mov_b32_e32 v4, v12
	v_mov_b32_e32 v16, v14
	v_mov_b32_e32 v17, v10
	v_pk_add_f32 v[4:5], v[4:5], v[16:17]
	v_add_f32_e32 v8, v13, v15
	v_add_f32_e32 v10, v9, v11
	v_mov_b32_e32 v9, v4
	v_mov_b32_e32 v11, v5
	v_pk_add_f32 v[4:5], v[8:9], v[10:11]
	ds_bpermute_b32 v9, v155, v5
	ds_bpermute_b32 v8, v155, v4
	s_waitcnt lgkmcnt(0)
	v_pk_add_f32 v[48:49], v[4:5], v[8:9]
	v_add_u32_e32 v4, 16, v0
	v_ashrrev_i32_e32 v5, 31, v4
	v_lshlrev_b64 v[8:9], 7, v[4:5]
	v_lshl_add_u64 v[12:13], v[6:7], 0, v[8:9]
	v_mov_b32_e32 v8, v124
	v_mov_b32_e32 v9, v125
	v_mov_b32_e32 v10, v126
	v_mov_b32_e32 v11, v127
	s_nop 0
	v_mov_b32_e32 v12, v180
	v_mov_b32_e32 v13, v181
	v_mov_b32_e32 v14, v182
	v_mov_b32_e32 v15, v183
	ds_bpermute_b32 v51, v157, v49
	ds_bpermute_b32 v50, v157, v48
	v_mov_b32_e32 v17, v8
	v_mov_b32_e32 v16, v12
	v_mov_b32_e32 v18, v14
	v_mov_b32_e32 v19, v10
	v_pk_add_f32 v[16:17], v[16:17], v[18:19]
	v_add_f32_e32 v8, v13, v15
	v_add_f32_e32 v10, v9, v11
	v_mov_b32_e32 v9, v16
	v_mov_b32_e32 v11, v17
	v_pk_add_f32 v[8:9], v[8:9], v[10:11]
	ds_bpermute_b32 v11, v155, v9
	ds_bpermute_b32 v10, v155, v8
	s_waitcnt lgkmcnt(0)
	v_pk_add_f32 v[52:53], v[8:9], v[10:11]
	v_add_u32_e32 v8, 32, v0
	v_ashrrev_i32_e32 v9, 31, v8
	v_lshlrev_b64 v[10:11], 7, v[8:9]
	v_lshl_add_u64 v[14:15], v[6:7], 0, v[10:11]
	v_mov_b32_e32 v10, v184
	v_mov_b32_e32 v11, v185
	v_mov_b32_e32 v12, v186
	v_mov_b32_e32 v13, v187
	s_nop 0
	v_mov_b32_e32 v14, v188
	v_mov_b32_e32 v15, v189
	v_mov_b32_e32 v16, v190
	v_mov_b32_e32 v17, v191
	ds_bpermute_b32 v55, v157, v53
	ds_bpermute_b32 v54, v157, v52
	v_mov_b32_e32 v19, v10
	v_mov_b32_e32 v18, v14
	v_mov_b32_e32 v20, v16
	v_mov_b32_e32 v21, v12
	v_pk_add_f32 v[18:19], v[18:19], v[20:21]
	v_add_f32_e32 v10, v15, v17
	v_add_f32_e32 v12, v11, v13
	v_mov_b32_e32 v11, v18
	v_mov_b32_e32 v13, v19
	v_pk_add_f32 v[10:11], v[10:11], v[12:13]
	ds_bpermute_b32 v13, v155, v11
	ds_bpermute_b32 v12, v155, v10
	s_waitcnt lgkmcnt(0)
	v_pk_add_f32 v[64:65], v[10:11], v[12:13]
	v_add_u32_e32 v10, 48, v0
	v_ashrrev_i32_e32 v11, 31, v10
	v_lshlrev_b64 v[12:13], 7, v[10:11]
	v_lshl_add_u64 v[16:17], v[6:7], 0, v[12:13]
	v_mov_b32_e32 v12, v192
	v_mov_b32_e32 v13, v193
	v_mov_b32_e32 v14, v194
	v_mov_b32_e32 v15, v195
	s_nop 0
	v_mov_b32_e32 v16, v196
	v_mov_b32_e32 v17, v197
	v_mov_b32_e32 v18, v198
	v_mov_b32_e32 v19, v199
	ds_bpermute_b32 v67, v157, v65
	ds_bpermute_b32 v66, v157, v64
	v_mov_b32_e32 v21, v12
	v_mov_b32_e32 v20, v16
	v_mov_b32_e32 v22, v18
	v_mov_b32_e32 v23, v14
	v_pk_add_f32 v[20:21], v[20:21], v[22:23]
	v_add_f32_e32 v12, v17, v19
	v_add_f32_e32 v14, v13, v15
	v_mov_b32_e32 v13, v20
	v_mov_b32_e32 v15, v21
	v_pk_add_f32 v[12:13], v[12:13], v[14:15]
	ds_bpermute_b32 v15, v155, v13
	ds_bpermute_b32 v14, v155, v12
	s_waitcnt lgkmcnt(0)
	v_pk_add_f32 v[68:69], v[12:13], v[14:15]
	v_add_u32_e32 v12, 0x80, v0
	v_ashrrev_i32_e32 v13, 31, v12
	v_lshlrev_b64 v[14:15], 7, v[12:13]
	v_lshl_add_u64 v[18:19], v[6:7], 0, v[14:15]
	v_mov_b32_e32 v14, v200
	v_mov_b32_e32 v15, v201
	v_mov_b32_e32 v16, v202
	v_mov_b32_e32 v17, v203
	s_nop 0
	v_mov_b32_e32 v18, v204
	v_mov_b32_e32 v19, v205
	v_mov_b32_e32 v20, v206
	v_mov_b32_e32 v21, v207
	v_lshlrev_b64 v[0:1], 11, v[0:1]
	v_lshl_add_u64 v[0:1], s[44:45], 0, v[0:1]
	ds_bpermute_b32 v71, v157, v69
	ds_bpermute_b32 v70, v157, v68
	v_mov_b32_e32 v23, v14
	v_mov_b32_e32 v22, v18
	v_mov_b32_e32 v24, v20
	v_mov_b32_e32 v25, v16
	v_pk_add_f32 v[22:23], v[22:23], v[24:25]
	v_add_f32_e32 v14, v19, v21
	v_add_f32_e32 v16, v15, v17
	v_mov_b32_e32 v15, v22
	v_mov_b32_e32 v17, v23
	v_pk_add_f32 v[14:15], v[14:15], v[16:17]
	ds_bpermute_b32 v17, v155, v15
	ds_bpermute_b32 v16, v155, v14
	s_waitcnt lgkmcnt(0)
	v_pk_add_f32 v[112:113], v[14:15], v[16:17]
	v_lshlrev_b64 v[14:15], 7, v[56:57]
	v_lshl_add_u64 v[18:19], v[6:7], 0, v[14:15]
	v_mov_b32_e32 v14, v208
	v_mov_b32_e32 v15, v209
	v_mov_b32_e32 v16, v210
	v_mov_b32_e32 v17, v211
	s_nop 0
	v_mov_b32_e32 v18, v212
	v_mov_b32_e32 v19, v213
	v_mov_b32_e32 v20, v214
	v_mov_b32_e32 v21, v215
	ds_bpermute_b32 v115, v157, v113
	ds_bpermute_b32 v114, v157, v112
	v_mov_b32_e32 v23, v14
	v_mov_b32_e32 v22, v18
	v_mov_b32_e32 v24, v20
	v_mov_b32_e32 v25, v16
	v_pk_add_f32 v[22:23], v[22:23], v[24:25]
	v_add_f32_e32 v14, v19, v21
	v_add_f32_e32 v16, v15, v17
	v_mov_b32_e32 v15, v22
	v_mov_b32_e32 v17, v23
	v_pk_add_f32 v[14:15], v[14:15], v[16:17]
	ds_bpermute_b32 v17, v155, v15
	ds_bpermute_b32 v16, v155, v14
	s_waitcnt lgkmcnt(0)
	v_pk_add_f32 v[116:117], v[14:15], v[16:17]
	v_lshlrev_b64 v[14:15], 7, v[58:59]
	v_lshl_add_u64 v[18:19], v[6:7], 0, v[14:15]
	v_mov_b32_e32 v14, v216
	v_mov_b32_e32 v15, v217
	v_mov_b32_e32 v16, v218
	v_mov_b32_e32 v17, v219
	s_nop 0
	v_mov_b32_e32 v18, v220
	v_mov_b32_e32 v19, v221
	v_mov_b32_e32 v20, v222
	v_mov_b32_e32 v21, v223
	ds_bpermute_b32 v119, v157, v117
	ds_bpermute_b32 v118, v157, v116
	v_mov_b32_e32 v23, v14
	v_mov_b32_e32 v22, v18
	v_mov_b32_e32 v24, v20
	v_mov_b32_e32 v25, v16
	v_pk_add_f32 v[22:23], v[22:23], v[24:25]
	v_add_f32_e32 v14, v19, v21
	v_add_f32_e32 v16, v15, v17
	v_mov_b32_e32 v15, v22
	v_mov_b32_e32 v17, v23
	v_pk_add_f32 v[14:15], v[14:15], v[16:17]
	ds_bpermute_b32 v17, v155, v15
	ds_bpermute_b32 v16, v155, v14
	s_waitcnt lgkmcnt(0)
	v_pk_add_f32 v[120:121], v[14:15], v[16:17]
	v_lshlrev_b64 v[14:15], 7, v[60:61]
	v_lshl_add_u64 v[6:7], v[6:7], 0, v[14:15]
	v_mov_b32_e32 v14, v224
	v_mov_b32_e32 v15, v225
	v_mov_b32_e32 v16, v226
	v_mov_b32_e32 v17, v227
	v_mov_b32_e32 v18, v228
	v_mov_b32_e32 v19, v229
	v_mov_b32_e32 v20, v230
	v_mov_b32_e32 v21, v231
	ds_bpermute_b32 v123, v157, v121
	ds_bpermute_b32 v122, v157, v120
	v_mov_b32_e32 v7, v14
	v_mov_b32_e32 v6, v18
	v_mov_b32_e32 v22, v20
	v_mov_b32_e32 v23, v16
	v_pk_add_f32 v[6:7], v[6:7], v[22:23]
	v_add_f32_e32 v14, v19, v21
	v_add_f32_e32 v16, v15, v17
	v_mov_b32_e32 v15, v6
	v_mov_b32_e32 v17, v7
	v_pk_add_f32 v[6:7], v[14:15], v[16:17]
	ds_bpermute_b32 v15, v155, v7
	ds_bpermute_b32 v14, v155, v6
	s_waitcnt lgkmcnt(0)
	v_pk_add_f32 v[124:125], v[6:7], v[14:15]
	v_lshlrev_b64 v[6:7], 2, v[2:3]
	v_lshlrev_b64 v[2:3], 1, v[2:3]
	v_lshl_add_u64 v[74:75], v[0:1], 0, v[2:3]
	v_lshlrev_b64 v[0:1], 11, v[4:5]
	v_lshl_add_u64 v[0:1], s[44:45], 0, v[0:1]
	v_lshl_add_u64 v[76:77], v[0:1], 0, v[2:3]
	v_lshlrev_b64 v[0:1], 11, v[8:9]
	v_lshl_add_u64 v[0:1], s[44:45], 0, v[0:1]
	v_lshl_add_u64 v[78:79], v[0:1], 0, v[2:3]
	v_lshlrev_b64 v[0:1], 11, v[10:11]
	v_lshl_add_u64 v[0:1], s[44:45], 0, v[0:1]
	v_lshl_add_u64 v[80:81], v[0:1], 0, v[2:3]
	v_lshlrev_b64 v[0:1], 11, v[12:13]
	v_lshl_add_u64 v[0:1], s[44:45], 0, v[0:1]
	v_lshl_add_u64 v[146:147], v[0:1], 0, v[2:3]
	v_lshlrev_b64 v[0:1], 11, v[56:57]
	v_lshl_add_u64 v[0:1], s[44:45], 0, v[0:1]
	v_lshl_add_u64 v[56:57], v[0:1], 0, v[2:3]
	v_lshlrev_b64 v[0:1], 11, v[58:59]
	v_lshl_add_u64 v[0:1], s[44:45], 0, v[0:1]
	v_lshl_add_u64 v[58:59], v[0:1], 0, v[2:3]
	v_lshlrev_b64 v[0:1], 11, v[60:61]
	v_lshl_add_u64 v[0:1], s[44:45], 0, v[0:1]
	v_lshl_add_u64 v[62:63], s[10:11], 0, v[6:7]
	v_lshl_add_u64 v[72:73], s[0:1], 0, v[6:7]
	v_lshl_add_u64 v[148:149], v[0:1], 0, v[2:3]
	global_load_dwordx4 v[36:39], v[62:63], off offset:16
	global_load_dwordx4 v[44:47], v[62:63], off
	global_load_dwordx4 v[32:35], v[72:73], off offset:16
	global_load_dwordx4 v[40:43], v[72:73], off
	global_load_dwordx4 v[28:31], v[74:75], off
	global_load_dwordx4 v[24:27], v[76:77], off
	global_load_dwordx4 v[20:23], v[78:79], off
	global_load_dwordx4 v[16:19], v[80:81], off
	global_load_dwordx4 v[12:15], v[146:147], off
	global_load_dwordx4 v[8:11], v[56:57], off
	global_load_dwordx4 v[4:7], v[58:59], off
	global_load_dwordx4 v[0:3], v[148:149], off
	global_load_dwordx4 v[104:107], v[62:63], off offset:528
	global_load_dwordx4 v[108:111], v[62:63], off offset:512
	global_load_dwordx4 v[96:99], v[72:73], off offset:528
	global_load_dwordx4 v[100:103], v[72:73], off offset:512
	global_load_dwordx4 v[92:95], v[74:75], off offset:256
	global_load_dwordx4 v[88:91], v[76:77], off offset:256
	global_load_dwordx4 v[84:87], v[78:79], off offset:256
	s_nop 0
	global_load_dwordx4 v[80:83], v[80:81], off offset:256
	s_nop 0
	global_load_dwordx4 v[76:79], v[146:147], off offset:256
	global_load_dwordx4 v[72:75], v[56:57], off offset:256
	global_load_dwordx4 v[60:63], v[58:59], off offset:256
	s_nop 0
	global_load_dwordx4 v[56:59], v[148:149], off offset:256
	ds_bpermute_b32 v127, v157, v125
	ds_bpermute_b32 v126, v157, v124
	s_cbranch_vccnz .LBB0_2365
	s_barrier
	s_branch .LBB0_2365

.LBB0_2572:
	s_or_b64 exec, exec, s[46:47]
	s_and_b64 vcc, exec, s[10:11]
	s_mov_b64 s[10:11], -1
	s_cbranch_vccnz .LBB0_2541
	v_mov_b32_e32 v0, v153
	v_mov_b32_e32 v1, v151
	s_lshl_b32 s10, s78, 8
	s_add_i32 s10, s10, s15
	v_add_u32_e32 v0, s10, v0
	s_waitcnt lgkmcnt(0)
	v_lshlrev_b32_e32 v2, 3, v1
	v_ashrrev_i32_e32 v3, 31, v2
	v_ashrrev_i32_e32 v1, 31, v0
	v_lshl_add_u64 v[6:7], v[2:3], 2, s[62:63]
	v_lshlrev_b64 v[4:5], 7, v[0:1]
	v_lshl_add_u64 v[4:5], v[6:7], 0, v[4:5]
	v_mov_b32_e32 v100, v0
	v_ashrrev_i32_e32 v101, 31, v100
	v_lshlrev_b64 v[100:101], 7, v[100:101]
	v_lshl_add_u64 v[100:101], v[6:7], 0, v[100:101]
	global_load_dwordx4 v[104:107], v[100:101], off offset:16
	global_load_dwordx4 v[108:111], v[100:101], off
	v_add_u32_e32 v100, 0x10, v0
	v_ashrrev_i32_e32 v101, 31, v100
	v_lshlrev_b64 v[100:101], 7, v[100:101]
	v_lshl_add_u64 v[100:101], v[6:7], 0, v[100:101]
	global_load_dwordx4 v[124:127], v[100:101], off offset:16
	global_load_dwordx4 v[180:183], v[100:101], off
	v_add_u32_e32 v100, 0x20, v0
	v_ashrrev_i32_e32 v101, 31, v100
	v_lshlrev_b64 v[100:101], 7, v[100:101]
	v_lshl_add_u64 v[100:101], v[6:7], 0, v[100:101]
	global_load_dwordx4 v[184:187], v[100:101], off offset:16
	global_load_dwordx4 v[188:191], v[100:101], off
	v_add_u32_e32 v100, 0x30, v0
	v_ashrrev_i32_e32 v101, 31, v100
	v_lshlrev_b64 v[100:101], 7, v[100:101]
	v_lshl_add_u64 v[100:101], v[6:7], 0, v[100:101]
	global_load_dwordx4 v[192:195], v[100:101], off offset:16
	global_load_dwordx4 v[196:199], v[100:101], off
	v_add_u32_e32 v100, 0x80, v0
	v_ashrrev_i32_e32 v101, 31, v100
	v_lshlrev_b64 v[100:101], 7, v[100:101]
	v_lshl_add_u64 v[100:101], v[6:7], 0, v[100:101]
	global_load_dwordx4 v[200:203], v[100:101], off offset:16
	global_load_dwordx4 v[204:207], v[100:101], off
	v_add_u32_e32 v100, 0x90, v0
	v_ashrrev_i32_e32 v101, 31, v100
	v_lshlrev_b64 v[100:101], 7, v[100:101]
	v_lshl_add_u64 v[100:101], v[6:7], 0, v[100:101]
	global_load_dwordx4 v[208:211], v[100:101], off offset:16
	global_load_dwordx4 v[212:215], v[100:101], off
	v_add_u32_e32 v100, 0xa0, v0
	v_ashrrev_i32_e32 v101, 31, v100
	v_lshlrev_b64 v[100:101], 7, v[100:101]
	v_lshl_add_u64 v[100:101], v[6:7], 0, v[100:101]
	global_load_dwordx4 v[216:219], v[100:101], off offset:16
	global_load_dwordx4 v[220:223], v[100:101], off
	v_add_u32_e32 v100, 0xb0, v0
	v_ashrrev_i32_e32 v101, 31, v100
	v_lshlrev_b64 v[100:101], 7, v[100:101]
	v_lshl_add_u64 v[100:101], v[6:7], 0, v[100:101]
	global_load_dwordx4 v[224:227], v[100:101], off offset:16
	global_load_dwordx4 v[228:231], v[100:101], off
	s_waitcnt vmcnt(0)
	v_mov_b32_e32 v8, v104
	v_mov_b32_e32 v9, v105
	v_mov_b32_e32 v10, v106
	v_mov_b32_e32 v11, v107
	v_mov_b32_e32 v12, v108
	v_mov_b32_e32 v13, v109
	v_mov_b32_e32 v14, v110
	v_mov_b32_e32 v15, v111
	v_add_u32_e32 v56, 0x90, v0
	v_ashrrev_i32_e32 v57, 31, v56
	v_add_u32_e32 v58, 0xa0, v0
	v_ashrrev_i32_e32 v59, 31, v58
	v_add_u32_e32 v60, 0xb0, v0
	v_ashrrev_i32_e32 v61, 31, v60
	s_lshl_b32 s10, s73, 8
	s_or_b32 s10, s10, s66
	v_add_u32_e32 v2, s10, v2
	v_ashrrev_i32_e32 v3, 31, v2
	v_readlane_b32 s10, v255, 50
	v_readlane_b32 s11, v255, 51
	s_andn2_b64 vcc, exec, s[6:7]
	v_mov_b32_e32 v5, v8
	v_mov_b32_e32 v4, v12
	v_mov_b32_e32 v16, v14
	v_mov_b32_e32 v17, v10
	v_pk_add_f32 v[4:5], v[4:5], v[16:17]
	v_add_f32_e32 v8, v13, v15
	v_add_f32_e32 v10, v9, v11
	v_mov_b32_e32 v9, v4
	v_mov_b32_e32 v11, v5
	v_pk_add_f32 v[4:5], v[8:9], v[10:11]
	ds_bpermute_b32 v9, v155, v5
	ds_bpermute_b32 v8, v155, v4
	s_waitcnt lgkmcnt(0)
	v_pk_add_f32 v[48:49], v[4:5], v[8:9]
	v_add_u32_e32 v4, 16, v0
	v_ashrrev_i32_e32 v5, 31, v4
	v_lshlrev_b64 v[8:9], 7, v[4:5]
	v_lshl_add_u64 v[12:13], v[6:7], 0, v[8:9]
	v_mov_b32_e32 v8, v124
	v_mov_b32_e32 v9, v125
	v_mov_b32_e32 v10, v126
	v_mov_b32_e32 v11, v127
	s_nop 0
	v_mov_b32_e32 v12, v180
	v_mov_b32_e32 v13, v181
	v_mov_b32_e32 v14, v182
	v_mov_b32_e32 v15, v183
	ds_bpermute_b32 v51, v157, v49
	ds_bpermute_b32 v50, v157, v48
	v_mov_b32_e32 v17, v8
	v_mov_b32_e32 v16, v12
	v_mov_b32_e32 v18, v14
	v_mov_b32_e32 v19, v10
	v_pk_add_f32 v[16:17], v[16:17], v[18:19]
	v_add_f32_e32 v8, v13, v15
	v_add_f32_e32 v10, v9, v11
	v_mov_b32_e32 v9, v16
	v_mov_b32_e32 v11, v17
	v_pk_add_f32 v[8:9], v[8:9], v[10:11]
	ds_bpermute_b32 v11, v155, v9
	ds_bpermute_b32 v10, v155, v8
	s_waitcnt lgkmcnt(0)
	v_pk_add_f32 v[52:53], v[8:9], v[10:11]
	v_add_u32_e32 v8, 32, v0
	v_ashrrev_i32_e32 v9, 31, v8
	v_lshlrev_b64 v[10:11], 7, v[8:9]
	v_lshl_add_u64 v[14:15], v[6:7], 0, v[10:11]
	v_mov_b32_e32 v10, v184
	v_mov_b32_e32 v11, v185
	v_mov_b32_e32 v12, v186
	v_mov_b32_e32 v13, v187
	s_nop 0
	v_mov_b32_e32 v14, v188
	v_mov_b32_e32 v15, v189
	v_mov_b32_e32 v16, v190
	v_mov_b32_e32 v17, v191
	ds_bpermute_b32 v55, v157, v53
	ds_bpermute_b32 v54, v157, v52
	v_mov_b32_e32 v19, v10
	v_mov_b32_e32 v18, v14
	v_mov_b32_e32 v20, v16
	v_mov_b32_e32 v21, v12
	v_pk_add_f32 v[18:19], v[18:19], v[20:21]
	v_add_f32_e32 v10, v15, v17
	v_add_f32_e32 v12, v11, v13
	v_mov_b32_e32 v11, v18
	v_mov_b32_e32 v13, v19
	v_pk_add_f32 v[10:11], v[10:11], v[12:13]
	ds_bpermute_b32 v13, v155, v11
	ds_bpermute_b32 v12, v155, v10
	s_waitcnt lgkmcnt(0)
	v_pk_add_f32 v[64:65], v[10:11], v[12:13]
	v_add_u32_e32 v10, 48, v0
	v_ashrrev_i32_e32 v11, 31, v10
	v_lshlrev_b64 v[12:13], 7, v[10:11]
	v_lshl_add_u64 v[16:17], v[6:7], 0, v[12:13]
	v_mov_b32_e32 v12, v192
	v_mov_b32_e32 v13, v193
	v_mov_b32_e32 v14, v194
	v_mov_b32_e32 v15, v195
	s_nop 0
	v_mov_b32_e32 v16, v196
	v_mov_b32_e32 v17, v197
	v_mov_b32_e32 v18, v198
	v_mov_b32_e32 v19, v199
	ds_bpermute_b32 v67, v157, v65
	ds_bpermute_b32 v66, v157, v64
	v_mov_b32_e32 v21, v12
	v_mov_b32_e32 v20, v16
	v_mov_b32_e32 v22, v18
	v_mov_b32_e32 v23, v14
	v_pk_add_f32 v[20:21], v[20:21], v[22:23]
	v_add_f32_e32 v12, v17, v19
	v_add_f32_e32 v14, v13, v15
	v_mov_b32_e32 v13, v20
	v_mov_b32_e32 v15, v21
	v_pk_add_f32 v[12:13], v[12:13], v[14:15]
	ds_bpermute_b32 v15, v155, v13
	ds_bpermute_b32 v14, v155, v12
	s_waitcnt lgkmcnt(0)
	v_pk_add_f32 v[68:69], v[12:13], v[14:15]
	v_add_u32_e32 v12, 0x80, v0
	v_ashrrev_i32_e32 v13, 31, v12
	v_lshlrev_b64 v[14:15], 7, v[12:13]
	v_lshl_add_u64 v[18:19], v[6:7], 0, v[14:15]
	v_mov_b32_e32 v14, v200
	v_mov_b32_e32 v15, v201
	v_mov_b32_e32 v16, v202
	v_mov_b32_e32 v17, v203
	s_nop 0
	v_mov_b32_e32 v18, v204
	v_mov_b32_e32 v19, v205
	v_mov_b32_e32 v20, v206
	v_mov_b32_e32 v21, v207
	v_lshlrev_b64 v[0:1], 11, v[0:1]
	v_lshl_add_u64 v[0:1], s[44:45], 0, v[0:1]
	ds_bpermute_b32 v71, v157, v69
	ds_bpermute_b32 v70, v157, v68
	v_mov_b32_e32 v23, v14
	v_mov_b32_e32 v22, v18
	v_mov_b32_e32 v24, v20
	v_mov_b32_e32 v25, v16
	v_pk_add_f32 v[22:23], v[22:23], v[24:25]
	v_add_f32_e32 v14, v19, v21
	v_add_f32_e32 v16, v15, v17
	v_mov_b32_e32 v15, v22
	v_mov_b32_e32 v17, v23
	v_pk_add_f32 v[14:15], v[14:15], v[16:17]
	ds_bpermute_b32 v17, v155, v15
	ds_bpermute_b32 v16, v155, v14
	s_waitcnt lgkmcnt(0)
	v_pk_add_f32 v[112:113], v[14:15], v[16:17]
	v_lshlrev_b64 v[14:15], 7, v[56:57]
	v_lshl_add_u64 v[18:19], v[6:7], 0, v[14:15]
	v_mov_b32_e32 v14, v208
	v_mov_b32_e32 v15, v209
	v_mov_b32_e32 v16, v210
	v_mov_b32_e32 v17, v211
	s_nop 0
	v_mov_b32_e32 v18, v212
	v_mov_b32_e32 v19, v213
	v_mov_b32_e32 v20, v214
	v_mov_b32_e32 v21, v215
	ds_bpermute_b32 v115, v157, v113
	ds_bpermute_b32 v114, v157, v112
	v_mov_b32_e32 v23, v14
	v_mov_b32_e32 v22, v18
	v_mov_b32_e32 v24, v20
	v_mov_b32_e32 v25, v16
	v_pk_add_f32 v[22:23], v[22:23], v[24:25]
	v_add_f32_e32 v14, v19, v21
	v_add_f32_e32 v16, v15, v17
	v_mov_b32_e32 v15, v22
	v_mov_b32_e32 v17, v23
	v_pk_add_f32 v[14:15], v[14:15], v[16:17]
	ds_bpermute_b32 v17, v155, v15
	ds_bpermute_b32 v16, v155, v14
	s_waitcnt lgkmcnt(0)
	v_pk_add_f32 v[116:117], v[14:15], v[16:17]
	v_lshlrev_b64 v[14:15], 7, v[58:59]
	v_lshl_add_u64 v[18:19], v[6:7], 0, v[14:15]
	v_mov_b32_e32 v14, v216
	v_mov_b32_e32 v15, v217
	v_mov_b32_e32 v16, v218
	v_mov_b32_e32 v17, v219
	s_nop 0
	v_mov_b32_e32 v18, v220
	v_mov_b32_e32 v19, v221
	v_mov_b32_e32 v20, v222
	v_mov_b32_e32 v21, v223
	ds_bpermute_b32 v119, v157, v117
	ds_bpermute_b32 v118, v157, v116
	v_mov_b32_e32 v23, v14
	v_mov_b32_e32 v22, v18
	v_mov_b32_e32 v24, v20
	v_mov_b32_e32 v25, v16
	v_pk_add_f32 v[22:23], v[22:23], v[24:25]
	v_add_f32_e32 v14, v19, v21
	v_add_f32_e32 v16, v15, v17
	v_mov_b32_e32 v15, v22
	v_mov_b32_e32 v17, v23
	v_pk_add_f32 v[14:15], v[14:15], v[16:17]
	ds_bpermute_b32 v17, v155, v15
	ds_bpermute_b32 v16, v155, v14
	s_waitcnt lgkmcnt(0)
	v_pk_add_f32 v[120:121], v[14:15], v[16:17]
	v_lshlrev_b64 v[14:15], 7, v[60:61]
	v_lshl_add_u64 v[6:7], v[6:7], 0, v[14:15]
	v_mov_b32_e32 v14, v224
	v_mov_b32_e32 v15, v225
	v_mov_b32_e32 v16, v226
	v_mov_b32_e32 v17, v227
	v_mov_b32_e32 v18, v228
	v_mov_b32_e32 v19, v229
	v_mov_b32_e32 v20, v230
	v_mov_b32_e32 v21, v231
	ds_bpermute_b32 v123, v157, v121
	ds_bpermute_b32 v122, v157, v120
	v_mov_b32_e32 v7, v14
	v_mov_b32_e32 v6, v18
	v_mov_b32_e32 v22, v20
	v_mov_b32_e32 v23, v16
	v_pk_add_f32 v[6:7], v[6:7], v[22:23]
	v_add_f32_e32 v14, v19, v21
	v_add_f32_e32 v16, v15, v17
	v_mov_b32_e32 v15, v6
	v_mov_b32_e32 v17, v7
	v_pk_add_f32 v[6:7], v[14:15], v[16:17]
	ds_bpermute_b32 v15, v155, v7
	ds_bpermute_b32 v14, v155, v6
	s_waitcnt lgkmcnt(0)
	v_pk_add_f32 v[124:125], v[6:7], v[14:15]
	v_lshlrev_b64 v[6:7], 2, v[2:3]
	v_lshlrev_b64 v[2:3], 1, v[2:3]
	v_lshl_add_u64 v[74:75], v[0:1], 0, v[2:3]
	v_lshlrev_b64 v[0:1], 11, v[4:5]
	v_lshl_add_u64 v[0:1], s[44:45], 0, v[0:1]
	v_lshl_add_u64 v[76:77], v[0:1], 0, v[2:3]
	v_lshlrev_b64 v[0:1], 11, v[8:9]
	v_lshl_add_u64 v[0:1], s[44:45], 0, v[0:1]
	v_lshl_add_u64 v[78:79], v[0:1], 0, v[2:3]
	v_lshlrev_b64 v[0:1], 11, v[10:11]
	v_lshl_add_u64 v[0:1], s[44:45], 0, v[0:1]
	v_lshl_add_u64 v[80:81], v[0:1], 0, v[2:3]
	v_lshlrev_b64 v[0:1], 11, v[12:13]
	v_lshl_add_u64 v[0:1], s[44:45], 0, v[0:1]
	v_lshl_add_u64 v[146:147], v[0:1], 0, v[2:3]
	v_lshlrev_b64 v[0:1], 11, v[56:57]
	v_lshl_add_u64 v[0:1], s[44:45], 0, v[0:1]
	v_lshl_add_u64 v[56:57], v[0:1], 0, v[2:3]
	v_lshlrev_b64 v[0:1], 11, v[58:59]
	v_lshl_add_u64 v[0:1], s[44:45], 0, v[0:1]
	v_lshl_add_u64 v[58:59], v[0:1], 0, v[2:3]
	v_lshlrev_b64 v[0:1], 11, v[60:61]
	v_lshl_add_u64 v[0:1], s[44:45], 0, v[0:1]
	v_lshl_add_u64 v[62:63], s[10:11], 0, v[6:7]
	v_lshl_add_u64 v[72:73], s[0:1], 0, v[6:7]
	v_lshl_add_u64 v[148:149], v[0:1], 0, v[2:3]
	global_load_dwordx4 v[36:39], v[62:63], off offset:16
	global_load_dwordx4 v[44:47], v[62:63], off
	global_load_dwordx4 v[32:35], v[72:73], off offset:16
	global_load_dwordx4 v[40:43], v[72:73], off
	global_load_dwordx4 v[28:31], v[74:75], off
	global_load_dwordx4 v[24:27], v[76:77], off
	global_load_dwordx4 v[20:23], v[78:79], off
	global_load_dwordx4 v[16:19], v[80:81], off
	global_load_dwordx4 v[12:15], v[146:147], off
	global_load_dwordx4 v[8:11], v[56:57], off
	global_load_dwordx4 v[4:7], v[58:59], off
	global_load_dwordx4 v[0:3], v[148:149], off
	global_load_dwordx4 v[104:107], v[62:63], off offset:528
	global_load_dwordx4 v[108:111], v[62:63], off offset:512
	global_load_dwordx4 v[96:99], v[72:73], off offset:528
	global_load_dwordx4 v[100:103], v[72:73], off offset:512
	global_load_dwordx4 v[92:95], v[74:75], off offset:256
	global_load_dwordx4 v[88:91], v[76:77], off offset:256
	global_load_dwordx4 v[84:87], v[78:79], off offset:256
	s_nop 0
	global_load_dwordx4 v[80:83], v[80:81], off offset:256
	s_nop 0
	global_load_dwordx4 v[76:79], v[146:147], off offset:256
	global_load_dwordx4 v[72:75], v[56:57], off offset:256
	global_load_dwordx4 v[60:63], v[58:59], off offset:256
	s_nop 0
	global_load_dwordx4 v[56:59], v[148:149], off offset:256
	ds_bpermute_b32 v127, v157, v125
	ds_bpermute_b32 v126, v157, v124
	s_cbranch_vccnz .LBB0_2540
	s_barrier
	s_branch .LBB0_2540

.LBB0_3490:
	s_or_b64 exec, exec, s[0:1]
	s_waitcnt lgkmcnt(0)
	s_barrier
	v_readlane_b32 s0, v255, 11
	v_ashrrev_i32_e32 v0, 6, v254
	s_nop 0
	v_add_u32_e32 v0, s0, v0
	s_mov_b32 s0, 0x8000
	v_cmp_gt_i32_e32 vcc, s0, v0
	s_and_saveexec_b64 s[0:1], vcc
	s_cbranch_execz .LBB0_3493
	v_mbcnt_lo_u32_b32 v1, -1, 0
	v_mbcnt_hi_u32_b32 v1, -1, v1
	v_and_b32_e32 v2, 64, v1
	v_add_u32_e32 v2, 64, v2
	v_xor_b32_e32 v3, 1, v1
	v_cmp_lt_i32_e32 vcc, v3, v2
	s_add_u32 s0, s30, 0x3000
	s_addc_u32 s1, s31, 0
	v_cndmask_b32_e32 v3, v1, v3, vcc
	v_lshlrev_b32_e32 v22, 2, v3
	v_xor_b32_e32 v3, 2, v1
	v_cmp_lt_i32_e32 vcc, v3, v2
	v_and_b32_e32 v28, 63, v254
	s_add_u32 s2, s28, 0x3000
	v_cndmask_b32_e32 v3, v1, v3, vcc
	v_lshlrev_b32_e32 v23, 2, v3
	v_xor_b32_e32 v3, 4, v1
	v_cmp_lt_i32_e32 vcc, v3, v2
	v_lshlrev_b32_e32 v20, 5, v28
	v_mov_b32_e32 v21, 0
	v_cndmask_b32_e32 v3, v1, v3, vcc
	v_lshlrev_b32_e32 v24, 2, v3
	v_xor_b32_e32 v3, 8, v1
	v_cmp_lt_i32_e32 vcc, v3, v2
	s_addc_u32 s3, s29, 0
	v_or_b32_e32 v8, 16, v20
	v_cndmask_b32_e32 v3, v1, v3, vcc
	v_lshlrev_b32_e32 v25, 2, v3
	v_xor_b32_e32 v3, 16, v1
	v_cmp_lt_i32_e32 vcc, v3, v2
	v_mov_b32_e32 v9, v21
	v_or_b32_e32 v12, 0x800, v20
	v_cndmask_b32_e32 v3, v1, v3, vcc
	v_lshlrev_b32_e32 v26, 2, v3
	v_xor_b32_e32 v3, 32, v1
	v_cmp_lt_i32_e32 vcc, v3, v2
	v_mov_b32_e32 v13, v21
	v_or_b32_e32 v16, 0x810, v20
	v_cndmask_b32_e32 v1, v1, v3, vcc
	v_lshlrev_b32_e32 v27, 2, v1
	v_ashrrev_i32_e32 v1, 31, v0
	v_lshlrev_b64 v[18:19], 11, v[0:1]
	v_mov_b32_e32 v17, v21
	v_lshl_or_b32 v18, v28, 4, v18
	v_lshlrev_b64 v[28:29], 12, v[0:1]
	v_lshl_add_u64 v[4:5], s[0:1], 0, v[20:21]
	v_lshl_add_u64 v[6:7], s[2:3], 0, v[8:9]
	v_lshl_add_u64 v[8:9], s[0:1], 0, v[8:9]
	v_lshl_add_u64 v[10:11], s[2:3], 0, v[12:13]
	v_lshl_add_u64 v[12:13], s[0:1], 0, v[12:13]
	v_lshl_add_u64 v[14:15], s[2:3], 0, v[16:17]
	v_lshl_add_u64 v[16:17], s[0:1], 0, v[16:17]
	v_lshl_add_u64 v[18:19], s[58:59], 0, v[18:19]
	s_mov_b64 s[0:1], 0x4000400
	s_ashr_i32 s97, s96, 31
	v_or_b32_e32 v28, v28, v20
	v_lshl_add_u64 v[2:3], s[2:3], 0, v[20:21]
	v_lshl_add_u64 v[18:19], v[18:19], 0, s[0:1]
	s_lshl_b64 s[2:3], s[96:97], 11
	v_lshl_add_u64 v[20:21], s[56:57], 0, v[28:29]
	s_lshl_b64 s[4:5], s[96:97], 12
	s_mov_b64 s[6:7], 0
	s_mov_b32 s8, 0xba800000
	v_mov_b32_e32 v1, 0x3727c5ac
	s_mov_b32 s9, 0xf800000
	v_mov_b32_e32 v28, 0x260
	s_movk_i32 s10, 0x7fff
	global_load_dwordx4 v[104:107], v[18:19], off offset:-1024
	global_load_dwordx4 v[108:111], v[18:19], off
	global_load_dwordx4 v[72:75], v[2:3], off
	global_load_dwordx4 v[76:79], v[4:5], off
	global_load_dwordx4 v[80:83], v[6:7], off
	global_load_dwordx4 v[84:87], v[8:9], off
	global_load_dwordx4 v[88:91], v[10:11], off
	global_load_dwordx4 v[92:95], v[12:13], off
	global_load_dwordx4 v[96:99], v[14:15], off
	global_load_dwordx4 v[100:103], v[16:17], off
	s_waitcnt vmcnt(0)
.LBB0_3492:
	s_waitcnt vmcnt(4)
	v_mov_b32_e32 v30, v104
	v_mov_b32_e32 v31, v105
	v_mov_b32_e32 v32, v106
	v_mov_b32_e32 v33, v107
	v_mov_b32_e32 v34, v108
	v_mov_b32_e32 v35, v109
	v_mov_b32_e32 v36, v110
	v_mov_b32_e32 v37, v111
	v_add_u32_e32 v0, s96, v0
	v_lshl_add_u64 v[18:19], v[18:19], 0, s[2:3]
	global_load_dwordx4 v[104:107], v[18:19], off offset:-1024
	global_load_dwordx4 v[108:111], v[18:19], off
	v_mov_b32_e32 v38, v72
	v_mov_b32_e32 v39, v73
	v_mov_b32_e32 v40, v74
	v_mov_b32_e32 v41, v75
	v_mov_b32_e32 v42, v76
	v_mov_b32_e32 v43, v77
	v_mov_b32_e32 v44, v78
	v_mov_b32_e32 v45, v79
	v_cvt_f32_f16_sdwa v46, v30 dst_sel:DWORD dst_unused:UNUSED_PAD src0_sel:WORD_1
	v_cvt_f32_f16_e32 v48, v30
	v_cvt_f32_f16_sdwa v47, v31 dst_sel:DWORD dst_unused:UNUSED_PAD src0_sel:WORD_1
	v_cvt_f32_f16_e32 v49, v31
	v_cvt_f32_f16_sdwa v50, v32 dst_sel:DWORD dst_unused:UNUSED_PAD src0_sel:WORD_1
	v_cvt_f32_f16_e32 v52, v32
	v_cvt_f32_f16_sdwa v51, v33 dst_sel:DWORD dst_unused:UNUSED_PAD src0_sel:WORD_1
	v_cvt_f32_f16_e32 v53, v33
	v_cvt_f32_f16_sdwa v29, v34 dst_sel:DWORD dst_unused:UNUSED_PAD src0_sel:WORD_1
	v_cvt_f32_f16_e32 v55, v34
	v_cvt_f32_f16_sdwa v59, v35 dst_sel:DWORD dst_unused:UNUSED_PAD src0_sel:WORD_1
	v_cvt_f32_f16_e32 v61, v35
	v_cvt_f32_f16_sdwa v54, v36 dst_sel:DWORD dst_unused:UNUSED_PAD src0_sel:WORD_1
	v_cvt_f32_f16_e32 v56, v36
	v_cvt_f32_f16_sdwa v58, v37 dst_sel:DWORD dst_unused:UNUSED_PAD src0_sel:WORD_1
	v_cvt_f32_f16_e32 v60, v37
	v_pk_add_f32 v[46:47], v[48:49], v[46:47]
	v_pk_add_f32 v[48:49], v[52:53], v[50:51]
	v_add_f32_e32 v57, v55, v29
	v_add_f32_e32 v29, v46, v47
	v_pk_add_f32 v[46:47], v[48:49], v[48:49] op_sel_hi:[0,1]
	v_add_f32_e32 v55, v61, v59
	v_add_f32_e32 v59, 0, v29
	v_mov_b32_e32 v61, v47
	v_pk_add_f32 v[48:49], v[56:57], v[54:55]
	v_pk_add_f32 v[46:47], v[60:61], v[58:59]
	s_nop 0
	v_pk_add_f32 v[46:47], v[48:49], v[46:47]
	s_nop 0
	v_add_f32_e32 v29, v46, v47
	ds_bpermute_b32 v46, v22, v29
	s_waitcnt lgkmcnt(0)
	v_add_f32_e32 v29, v29, v46
	ds_bpermute_b32 v46, v23, v29
	s_waitcnt lgkmcnt(0)
	v_add_f32_e32 v29, v29, v46
	ds_bpermute_b32 v46, v24, v29
	s_waitcnt lgkmcnt(0)
	v_add_f32_e32 v29, v29, v46
	ds_bpermute_b32 v46, v25, v29
	s_waitcnt lgkmcnt(0)
	v_add_f32_e32 v29, v29, v46
	ds_bpermute_b32 v46, v26, v29
	s_waitcnt lgkmcnt(0)
	v_add_f32_e32 v29, v29, v46
	ds_bpermute_b32 v46, v27, v29
	s_waitcnt lgkmcnt(0)
	v_add_f32_e32 v29, v29, v46
	v_fma_mix_f32 v47, v29, s8, v30 op_sel:[0,0,1] op_sel_hi:[0,0,1]
	v_fma_mix_f32 v46, v29, s8, v30 op_sel_hi:[0,0,1]
	v_fma_mix_f32 v49, v29, s8, v31 op_sel:[0,0,1] op_sel_hi:[0,0,1]
	v_fma_mix_f32 v48, v29, s8, v31 op_sel_hi:[0,0,1]
	v_fma_mix_f32 v51, v29, s8, v32 op_sel:[0,0,1] op_sel_hi:[0,0,1]
	v_fma_mix_f32 v50, v29, s8, v32 op_sel_hi:[0,0,1]
	v_fma_mix_f32 v53, v29, s8, v33 op_sel:[0,0,1] op_sel_hi:[0,0,1]
	v_fma_mix_f32 v52, v29, s8, v33 op_sel_hi:[0,0,1]
	v_fma_mix_f32 v55, v29, s8, v34 op_sel:[0,0,1] op_sel_hi:[0,0,1]
	v_fma_mix_f32 v54, v29, s8, v34 op_sel_hi:[0,0,1]
	v_fma_mix_f32 v57, v29, s8, v35 op_sel:[0,0,1] op_sel_hi:[0,0,1]
	v_fma_mix_f32 v56, v29, s8, v35 op_sel_hi:[0,0,1]
	v_fma_mix_f32 v59, v29, s8, v37 op_sel:[0,0,1] op_sel_hi:[0,0,1]
	v_fma_mix_f32 v58, v29, s8, v37 op_sel_hi:[0,0,1]
	v_fma_mix_f32 v61, v29, s8, v36 op_sel:[0,0,1] op_sel_hi:[0,0,1]
	v_fma_mix_f32 v60, v29, s8, v36 op_sel_hi:[0,0,1]
	v_pk_mul_f32 v[30:31], v[48:49], v[48:49]
	v_pk_mul_f32 v[32:33], v[46:47], v[46:47]
	v_pk_mul_f32 v[34:35], v[52:53], v[52:53]
	v_pk_mul_f32 v[36:37], v[50:51], v[50:51]
	v_pk_mov_b32 v[66:67], v[32:33], v[30:31] op_sel:[1,0]
	v_mov_b32_e32 v33, v31
	v_pk_mov_b32 v[30:31], v[36:37], v[34:35] op_sel:[1,0]
	v_mov_b32_e32 v37, v35
	v_mul_f32_e32 v62, v54, v54
	v_mul_f32_e32 v64, v56, v56
	v_pk_add_f32 v[32:33], v[66:67], v[32:33]
	v_pk_add_f32 v[30:31], v[30:31], v[36:37]
	v_pk_fma_f32 v[34:35], v[54:55], v[54:55], v[62:63] op_sel_hi:[1,1,0]
	v_pk_fma_f32 v[62:63], v[56:57], v[56:57], v[64:65] op_sel_hi:[1,1,0]
	v_pk_add_f32 v[32:33], v[32:33], v[32:33] op_sel_hi:[0,1]
	v_pk_add_f32 v[30:31], v[30:31], v[30:31] op_sel_hi:[0,1]
	v_mul_f32_e32 v34, v60, v60
	v_mul_f32_e32 v62, v61, v61
	v_mul_f32_e32 v32, v58, v58
	v_mul_f32_e32 v30, v59, v59
	v_pk_add_f32 v[34:35], v[34:35], v[62:63]
	v_pk_add_f32 v[30:31], v[32:33], v[30:31]
	s_nop 0
	v_pk_add_f32 v[30:31], v[34:35], v[30:31]
	s_nop 0
	v_add_f32_e32 v29, v30, v31
	ds_bpermute_b32 v30, v22, v29
	s_waitcnt lgkmcnt(0)
	v_add_f32_e32 v29, v29, v30
	ds_bpermute_b32 v30, v23, v29
	s_waitcnt lgkmcnt(0)
	v_add_f32_e32 v29, v29, v30
	ds_bpermute_b32 v30, v24, v29
	s_waitcnt lgkmcnt(0)
	v_add_f32_e32 v29, v29, v30
	ds_bpermute_b32 v30, v25, v29
	s_waitcnt lgkmcnt(0)
	v_add_f32_e32 v29, v29, v30
	ds_bpermute_b32 v30, v26, v29
	s_waitcnt lgkmcnt(0)
	v_add_f32_e32 v29, v29, v30
	ds_bpermute_b32 v30, v27, v29
	s_waitcnt lgkmcnt(0)
	v_add_f32_e32 v29, v29, v30
	v_fmamk_f32 v29, v29, 0x3a800000, v1
	v_mul_f32_e32 v30, 0x4f800000, v29
	v_cmp_gt_f32_e32 vcc, s9, v29
	s_nop 1
	v_cndmask_b32_e32 v29, v29, v30, vcc
	v_sqrt_f32_e32 v30, v29
	s_nop 0
	v_add_u32_e32 v31, -1, v30
	v_add_u32_e32 v32, 1, v30
	v_fma_f32 v33, -v31, v30, v29
	v_fma_f32 v34, -v32, v30, v29
	v_cmp_ge_f32_e64 s[0:1], 0, v33
	s_nop 1
	v_cndmask_b32_e64 v30, v30, v31, s[0:1]
	v_cmp_lt_f32_e64 s[0:1], 0, v34
	s_nop 1
	v_cndmask_b32_e64 v30, v30, v32, s[0:1]
	v_mul_f32_e32 v31, 0x37800000, v30
	v_cndmask_b32_e32 v30, v30, v31, vcc
	v_cmp_class_f32_e32 vcc, v29, v28
	s_nop 1
	v_cndmask_b32_e32 v29, v30, v29, vcc
	v_div_scale_f32 v30, s[0:1], v29, v29, 1.0
	v_rcp_f32_e32 v32, v30
	v_div_scale_f32 v31, vcc, 1.0, v29, 1.0
	v_fma_f32 v33, -v30, v32, 1.0
	v_fmac_f32_e32 v32, v33, v32
	v_mul_f32_e32 v33, v31, v32
	v_fma_f32 v34, -v30, v33, v31
	v_fmac_f32_e32 v33, v34, v32
	v_fma_f32 v30, -v30, v33, v31
	v_div_fmas_f32 v30, v30, v32, v33
	v_div_fixup_f32 v62, v30, v29, 1.0
	v_pk_mul_f32 v[30:31], v[46:47], v[62:63] op_sel_hi:[1,0]
	v_pk_mul_f32 v[32:33], v[48:49], v[62:63] op_sel_hi:[1,0]
	v_pk_fma_f32 v[30:31], v[38:39], v[30:31], v[42:43]
	v_pk_fma_f32 v[32:33], v[40:41], v[32:33], v[44:45]
	global_store_dwordx4 v[20:21], v[30:33], off
	s_nop 1
	v_mov_b32_e32 v30, v80
	v_mov_b32_e32 v31, v81
	v_mov_b32_e32 v32, v82
	v_mov_b32_e32 v33, v83
	s_nop 0
	v_mov_b32_e32 v34, v84
	v_mov_b32_e32 v35, v85
	v_mov_b32_e32 v36, v86
	v_mov_b32_e32 v37, v87
	v_pk_mul_f32 v[38:39], v[52:53], v[62:63] op_sel_hi:[1,0]
	v_pk_mul_f32 v[40:41], v[50:51], v[62:63] op_sel_hi:[1,0]
	v_cmp_lt_i32_e32 vcc, s10, v0
	s_or_b64 s[6:7], vcc, s[6:7]
	v_pk_fma_f32 v[30:31], v[30:31], v[40:41], v[34:35]
	v_pk_fma_f32 v[32:33], v[32:33], v[38:39], v[36:37]
	global_store_dwordx4 v[20:21], v[30:33], off offset:16
	s_nop 1
	v_mov_b32_e32 v30, v88
	v_mov_b32_e32 v31, v89
	v_mov_b32_e32 v32, v90
	v_mov_b32_e32 v33, v91
	s_nop 0
	v_mov_b32_e32 v34, v92
	v_mov_b32_e32 v35, v93
	v_mov_b32_e32 v36, v94
	v_mov_b32_e32 v37, v95
	v_pk_mul_f32 v[38:39], v[56:57], v[62:63] op_sel_hi:[1,0]
	v_pk_mul_f32 v[40:41], v[54:55], v[62:63] op_sel_hi:[1,0]
	v_pk_fma_f32 v[32:33], v[32:33], v[38:39], v[36:37]
	v_pk_fma_f32 v[30:31], v[30:31], v[40:41], v[34:35]
	global_store_dwordx4 v[20:21], v[30:33], off offset:2048
	s_nop 1
	v_mov_b32_e32 v30, v96
	v_mov_b32_e32 v31, v97
	v_mov_b32_e32 v32, v98
	v_mov_b32_e32 v33, v99
	s_nop 0
	v_mov_b32_e32 v34, v100
	v_mov_b32_e32 v35, v101
	v_mov_b32_e32 v36, v102
	v_mov_b32_e32 v37, v103
	v_pk_mul_f32 v[38:39], v[58:59], v[62:63] op_sel_hi:[1,0]
	v_pk_mul_f32 v[40:41], v[60:61], v[62:63] op_sel_hi:[1,0]
	v_pk_fma_f32 v[32:33], v[32:33], v[38:39], v[36:37]
	v_pk_fma_f32 v[30:31], v[30:31], v[40:41], v[34:35]
	global_store_dwordx4 v[20:21], v[30:33], off offset:2064
	v_lshl_add_u64 v[20:21], v[20:21], 0, s[4:5]
	s_andn2_b64 exec, exec, s[6:7]
	s_cbranch_execnz .LBB0_3492
